# GEMM MFMA blocks: two K-halves of each accumulator issued back to back (same-accumulator chain) instead of 8 MFMAs apart
# speedup vs baseline: 1.0080x; 1.0053x over previous
; #define PG8_STAGE(bufoff, gbase, voff) do { _Pragma("unroll") for (int _i = 0; _i < 2; ++_i) \
;         __builtin_amdgcn_global_load_lds((const unsigned*)((const char*)(gbase) + (voff)[_i]), (PG8_LAS unsigned*)(lds + (bufoff) + ldsw + _i * 8192), 16, 0, 0); } while (0)
; #define PG8_LDA(dst, b, h) do { _Pragma("unroll") for (int m = 0; m < 4; ++m) _Pragma("unroll") for (int k = 0; k < 2; ++k) dst[m][k] = *(const PG8_LAS bf16x8*)(lds + PG8_SA(b, h) + aoff + m * 2048 + k * 1024); } while (0)
; #define PG8_LDB(dst, b, h) do { _Pragma("unroll") for (int n = 0; n < 2; ++n) _Pragma("unroll") for (int k = 0; k < 2; ++k) dst[n][k] = *(const PG8_LAS bf16x8*)(lds + PG8_SB(b, h) + boff + n * 2048 + k * 1024); } while (0)
; #define PG8_MMA(ai, bj, At, Bt) do { __builtin_amdgcn_s_setprio(1); _Pragma("unroll") for (int m = 0; m < 4; ++m) _Pragma("unroll") for (int n = 0; n < 2; ++n) _Pragma("unroll") for (int k = 0; k < 2; ++k) \
;         acc[ai][bj][m][n] = __builtin_amdgcn_mfma_f32_16x16x32_bf16(Bt[n][k], At[m][k], acc[ai][bj][m][n], 0, 0, 0); __builtin_amdgcn_s_setprio(0); } while (0)
; #define PG8_WAIT_V(n) asm volatile("s_waitcnt vmcnt(" #n ")" ::: "memory")
; #define PG8_WAIT_L(n) asm volatile("s_waitcnt lgkmcnt(" #n ")" ::: "memory")
; #define PG8_BAR __builtin_amdgcn_s_barrier()
; #define PG8_SCHED __builtin_amdgcn_sched_barrier(0)
;     ...
;             const bool last = (t == nt - 2);
;             const char* a1 = cA + (size_t)(t + 1) * kstep;
;             const char* a2 = last ? nA : cA + (size_t)(t + 2) * kstep; const char* b2 = last ? nB : cB + (size_t)(t + 2) * kstep;
;             const char* a3 = a2 + kstep; const char* b3 = b2 + kstep;
;             if (last && has_next) S.a_ready(nxt);
;             if constexpr (SP2) {
;             PG8_LDB(B0, 0, 0); PG8_LDB(B1, 0, 1); PG8_SCHED; PG8_LDA(At, 0, 0); PG8_STAGE(PG8_SA(1, 1), a1 + hstepA, voffA);
;             PG8_WAIT_V(8); PG8_WAIT_L(0); PG8_BAR; PG8_MMA(0, 0, At, B0); PG8_MMA(0, 1, At, B1); PG8_BAR; PG8_SCHED;
;             PG8_LDA(At, 0, 1); PG8_STAGE(PG8_SB(0, 0), b2, voffB); PG8_STAGE(PG8_SB(0, 1), b2 + hstep, voffB); PG8_STAGE(PG8_SA(0, 0), a2, voffA);
;             PG8_WAIT_V(8); PG8_WAIT_L(0); PG8_BAR; PG8_MMA(1, 0, At, B0); PG8_MMA(1, 1, At, B1); PG8_BAR; PG8_SCHED;
.LBB0_407:
	s_add_u32 s28, s30, 0xfff80080
	s_addc_u32 s29, s31, -1
	s_add_i32 s42, 0, 0x10000
	s_cmp_eq_u32 s93, 28
	s_cselect_b32 vcc_hi, s9, s29
	s_cselect_b32 vcc_lo, s25, s28
	v_add_u32_e32 v32, s42, v180
	s_cselect_b32 s29, s33, s50
	s_cselect_b32 s28, s40, s48
	s_add_i32 s46, 0, 0x14000
	ds_read_b128 v[136:139], v32
	ds_read_b128 v[140:143], v32 offset:1024
	ds_read_b128 v[144:147], v32 offset:2048
	ds_read_b128 v[148:151], v32 offset:3072
	v_add_u32_e32 v32, s46, v180
	ds_read_b128 v[166:169], v32
	ds_read_b128 v[170:173], v32 offset:1024
	ds_read_b128 v[174:177], v32 offset:2048
	ds_read_b128 v[198:201], v32 offset:3072
	v_lshl_add_u64 v[34:35], s[30:31], 0, v[162:163]
	s_add_i32 m0, s17, 0xc000
	ds_read_b128 v[202:205], v196
	ds_read_b128 v[206:209], v196 offset:1024
	ds_read_b128 v[210:213], v196 offset:2048
	ds_read_b128 v[214:217], v196 offset:3072
	ds_read_b128 v[218:221], v196 offset:4096
	ds_read_b128 v[222:225], v196 offset:5120
	ds_read_b128 v[226:229], v196 offset:6144
	ds_read_b128 v[240:243], v196 offset:7168
	global_load_lds_dwordx4 v[34:35], off
	v_lshl_add_u64 v[34:35], s[30:31], 0, v[164:165]
	s_add_i32 m0, s17, 0xe000
	s_nop 0
	global_load_lds_dwordx4 v[34:35], off
	s_waitcnt vmcnt(8)
	s_waitcnt lgkmcnt(0)
	s_barrier
	s_setprio 1
	s_waitcnt lgkmcnt(0)
	v_mfma_f32_16x16x32_bf16 v[132:135], v[136:139], v[202:205], v[132:135]
	v_mfma_f32_16x16x32_bf16 v[132:135], v[140:143], v[206:209], v[132:135]
	v_mfma_f32_16x16x32_bf16 v[128:131], v[144:147], v[202:205], v[128:131]
	v_mfma_f32_16x16x32_bf16 v[128:131], v[148:151], v[206:209], v[128:131]
	v_mfma_f32_16x16x32_bf16 v[116:119], v[136:139], v[210:213], v[116:119]
	v_mfma_f32_16x16x32_bf16 v[116:119], v[140:143], v[214:217], v[116:119]
	v_mfma_f32_16x16x32_bf16 v[112:115], v[144:147], v[210:213], v[112:115]
	v_mfma_f32_16x16x32_bf16 v[112:115], v[148:151], v[214:217], v[112:115]
	v_mfma_f32_16x16x32_bf16 v[100:103], v[136:139], v[218:221], v[100:103]
	v_mfma_f32_16x16x32_bf16 v[100:103], v[140:143], v[222:225], v[100:103]
	v_mfma_f32_16x16x32_bf16 v[96:99], v[144:147], v[218:221], v[96:99]
	v_mfma_f32_16x16x32_bf16 v[96:99], v[148:151], v[222:225], v[96:99]
	v_mfma_f32_16x16x32_bf16 v[84:87], v[136:139], v[226:229], v[84:87]
	v_mfma_f32_16x16x32_bf16 v[84:87], v[140:143], v[240:243], v[84:87]
	v_mfma_f32_16x16x32_bf16 v[80:83], v[144:147], v[226:229], v[80:83]
	v_mfma_f32_16x16x32_bf16 v[80:83], v[148:151], v[240:243], v[80:83]
	s_setprio 0
	s_setprio 1
	v_mfma_f32_16x16x32_bf16 v[124:127], v[166:169], v[202:205], v[124:127]
	v_mfma_f32_16x16x32_bf16 v[124:127], v[170:173], v[206:209], v[124:127]
	v_mfma_f32_16x16x32_bf16 v[120:123], v[174:177], v[202:205], v[120:123]
	v_mfma_f32_16x16x32_bf16 v[120:123], v[198:201], v[206:209], v[120:123]
	v_mfma_f32_16x16x32_bf16 v[108:111], v[166:169], v[210:213], v[108:111]
	v_mfma_f32_16x16x32_bf16 v[108:111], v[170:173], v[214:217], v[108:111]
	v_mfma_f32_16x16x32_bf16 v[104:107], v[174:177], v[210:213], v[104:107]
	v_mfma_f32_16x16x32_bf16 v[104:107], v[198:201], v[214:217], v[104:107]
	v_mfma_f32_16x16x32_bf16 v[92:95], v[166:169], v[218:221], v[92:95]
	v_mfma_f32_16x16x32_bf16 v[92:95], v[170:173], v[222:225], v[92:95]
	v_mfma_f32_16x16x32_bf16 v[88:91], v[174:177], v[218:221], v[88:91]
	v_mfma_f32_16x16x32_bf16 v[88:91], v[198:201], v[222:225], v[88:91]
	v_mfma_f32_16x16x32_bf16 v[76:79], v[166:169], v[226:229], v[76:79]
	v_mfma_f32_16x16x32_bf16 v[76:79], v[170:173], v[240:243], v[76:79]
	v_mfma_f32_16x16x32_bf16 v[72:75], v[174:177], v[226:229], v[72:75]
	v_mfma_f32_16x16x32_bf16 v[72:75], v[198:201], v[240:243], v[72:75]
	s_setprio 0
	s_barrier
	s_add_i32 s42, s42, s41
	v_lshl_add_u64 v[178:179], s[28:29], 0, v[154:155]
	s_mov_b32 m0, s42
	ds_read_b128 v[202:205], v196 offset:16384
	ds_read_b128 v[206:209], v196 offset:17408
	ds_read_b128 v[210:213], v196 offset:18432
	ds_read_b128 v[214:217], v196 offset:19456
	ds_read_b128 v[218:221], v196 offset:20480
	ds_read_b128 v[222:225], v196 offset:21504
	ds_read_b128 v[226:229], v196 offset:22528
	ds_read_b128 v[240:243], v196 offset:23552
	global_load_lds_dwordx4 v[178:179], off
	s_add_i32 m0, s42, 0x2000
	s_add_u32 s42, s28, 0x80000
	v_lshl_add_u64 v[186:187], s[28:29], 0, v[158:159]
	s_addc_u32 s43, s29, 0
	s_add_i32 s46, s46, s41
	global_load_lds_dwordx4 v[186:187], off
	v_lshl_add_u64 v[34:35], s[42:43], 0, v[154:155]
	s_mov_b32 m0, s46
	v_lshl_add_u64 v[188:189], vcc, 0, v[152:153]
	global_load_lds_dwordx4 v[34:35], off
	v_lshl_add_u64 v[34:35], s[42:43], 0, v[158:159]
	s_add_i32 m0, s46, 0x2000
	v_lshl_add_u64 v[190:191], vcc, 0, v[156:157]
	global_load_lds_dwordx4 v[34:35], off
	s_mov_b32 m0, s17
	s_nop 0
	global_load_lds_dwordx4 v[188:189], off
	s_mov_b32 m0, s53
	s_nop 0
	global_load_lds_dwordx4 v[190:191], off
	s_waitcnt vmcnt(8)
	s_waitcnt lgkmcnt(0)
	s_barrier
; #define PG8_STAGE(bufoff, gbase, voff) do { _Pragma("unroll") for (int _i = 0; _i < 2; ++_i) \
;         __builtin_amdgcn_global_load_lds((const unsigned*)((const char*)(gbase) + (voff)[_i]), (PG8_LAS unsigned*)(lds + (bufoff) + ldsw + _i * 8192), 16, 0, 0); } while (0)
; #define PG8_LDA(dst, b, h) do { _Pragma("unroll") for (int m = 0; m < 4; ++m) _Pragma("unroll") for (int k = 0; k < 2; ++k) dst[m][k] = *(const PG8_LAS bf16x8*)(lds + PG8_SA(b, h) + aoff + m * 2048 + k * 1024); } while (0)
; #define PG8_LDB(dst, b, h) do { _Pragma("unroll") for (int n = 0; n < 2; ++n) _Pragma("unroll") for (int k = 0; k < 2; ++k) dst[n][k] = *(const PG8_LAS bf16x8*)(lds + PG8_SB(b, h) + boff + n * 2048 + k * 1024); } while (0)
; #define PG8_MMA(ai, bj, At, Bt) do { __builtin_amdgcn_s_setprio(1); _Pragma("unroll") for (int m = 0; m < 4; ++m) _Pragma("unroll") for (int n = 0; n < 2; ++n) _Pragma("unroll") for (int k = 0; k < 2; ++k) \
;         acc[ai][bj][m][n] = __builtin_amdgcn_mfma_f32_16x16x32_bf16(Bt[n][k], At[m][k], acc[ai][bj][m][n], 0, 0, 0); __builtin_amdgcn_s_setprio(0); } while (0)
; #define PG8_WAIT_V(n) asm volatile("s_waitcnt vmcnt(" #n ")" ::: "memory")
; #define PG8_WAIT_L(n) asm volatile("s_waitcnt lgkmcnt(" #n ")" ::: "memory")
; #define PG8_BAR __builtin_amdgcn_s_barrier()
; #define PG8_SCHED __builtin_amdgcn_sched_barrier(0)
;     ...
;             PG8_WAIT_V(8); PG8_WAIT_L(0); PG8_BAR; PG8_MMA(1, 0, At, B0); PG8_MMA(1, 1, At, B1); PG8_BAR; PG8_SCHED;
;             PG8_LDB(B0, 1, 0); PG8_LDB(B1, 1, 1); PG8_SCHED; PG8_LDA(At, 1, 0); PG8_STAGE(PG8_SA(0, 1), a2 + hstepA, voffA);
;             PG8_WAIT_V(8); PG8_WAIT_L(0); PG8_BAR; PG8_MMA(0, 0, At, B0); PG8_MMA(0, 1, At, B1); PG8_BAR; PG8_SCHED;
	s_setprio 1
	s_waitcnt lgkmcnt(0)
	v_mfma_f32_16x16x32_bf16 v[68:71], v[136:139], v[202:205], v[68:71]
	v_mfma_f32_16x16x32_bf16 v[68:71], v[140:143], v[206:209], v[68:71]
	v_mfma_f32_16x16x32_bf16 v[64:67], v[144:147], v[202:205], v[64:67]
	v_mfma_f32_16x16x32_bf16 v[64:67], v[148:151], v[206:209], v[64:67]
	v_mfma_f32_16x16x32_bf16 v[52:55], v[136:139], v[210:213], v[52:55]
	v_mfma_f32_16x16x32_bf16 v[52:55], v[140:143], v[214:217], v[52:55]
	v_mfma_f32_16x16x32_bf16 v[48:51], v[144:147], v[210:213], v[48:51]
	v_mfma_f32_16x16x32_bf16 v[48:51], v[148:151], v[214:217], v[48:51]
	v_mfma_f32_16x16x32_bf16 v[34:37], v[136:139], v[218:221], v[36:39]
	v_mfma_f32_16x16x32_bf16 v[34:37], v[140:143], v[222:225], v[34:37]
	v_mfma_f32_16x16x32_bf16 v[26:29], v[144:147], v[218:221], v[26:29]
	v_mfma_f32_16x16x32_bf16 v[26:29], v[148:151], v[222:225], v[26:29]
	v_mfma_f32_16x16x32_bf16 v[14:17], v[136:139], v[226:229], v[14:17]
	v_mfma_f32_16x16x32_bf16 v[14:17], v[140:143], v[240:243], v[14:17]
	v_mfma_f32_16x16x32_bf16 v[10:13], v[144:147], v[226:229], v[10:13]
	v_mfma_f32_16x16x32_bf16 v[10:13], v[148:151], v[240:243], v[10:13]
	s_setprio 0
	s_setprio 1
	v_mfma_f32_16x16x32_bf16 v[60:63], v[166:169], v[202:205], v[60:63]
	v_mfma_f32_16x16x32_bf16 v[60:63], v[170:173], v[206:209], v[60:63]
	v_mfma_f32_16x16x32_bf16 v[56:59], v[174:177], v[202:205], v[56:59]
	v_mfma_f32_16x16x32_bf16 v[56:59], v[198:201], v[206:209], v[56:59]
	v_mfma_f32_16x16x32_bf16 v[44:47], v[166:169], v[210:213], v[44:47]
	v_mfma_f32_16x16x32_bf16 v[44:47], v[170:173], v[214:217], v[44:47]
	v_mfma_f32_16x16x32_bf16 v[38:41], v[174:177], v[210:213], v[40:43]
	v_mfma_f32_16x16x32_bf16 v[40:43], v[198:201], v[214:217], v[38:41]
	v_mfma_f32_16x16x32_bf16 v[22:25], v[166:169], v[218:221], v[22:25]
	v_mfma_f32_16x16x32_bf16 v[22:25], v[170:173], v[222:225], v[22:25]
	v_mfma_f32_16x16x32_bf16 v[18:21], v[174:177], v[218:221], v[18:21]
	v_mfma_f32_16x16x32_bf16 v[18:21], v[198:201], v[222:225], v[18:21]
	v_mfma_f32_16x16x32_bf16 v[6:9], v[166:169], v[226:229], v[6:9]
	v_mfma_f32_16x16x32_bf16 v[6:9], v[170:173], v[240:243], v[6:9]
	v_mfma_f32_16x16x32_bf16 v[2:5], v[174:177], v[226:229], v[2:5]
	v_mfma_f32_16x16x32_bf16 v[2:5], v[198:201], v[240:243], v[2:5]
	s_setprio 0
	s_barrier
	s_add_i32 s46, 0, 0x18000
	v_add_u32_e32 v32, s46, v180
	s_add_i32 s47, 0, 0x1c000
	ds_read_b128 v[136:139], v32
	ds_read_b128 v[140:143], v32 offset:1024
	ds_read_b128 v[144:147], v32 offset:2048
	ds_read_b128 v[148:151], v32 offset:3072
	v_add_u32_e32 v32, s47, v180
	ds_read_b128 v[166:169], v32
	ds_read_b128 v[170:173], v32 offset:1024
	ds_read_b128 v[174:177], v32 offset:2048
	ds_read_b128 v[198:201], v32 offset:3072
	s_add_u32 s42, vcc_lo, 0x80000
	s_addc_u32 s43, vcc_hi, 0
	s_mov_b32 m0, s74
	v_lshl_add_u64 v[38:39], s[42:43], 0, v[152:153]
	ds_read_b128 v[202:205], v196 offset:32768
	ds_read_b128 v[206:209], v196 offset:33792
	ds_read_b128 v[210:213], v196 offset:34816
	ds_read_b128 v[214:217], v196 offset:35840
	ds_read_b128 v[218:221], v196 offset:36864
	ds_read_b128 v[222:225], v196 offset:37888
	ds_read_b128 v[226:229], v196 offset:38912
	ds_read_b128 v[240:243], v196 offset:39936
	global_load_lds_dwordx4 v[38:39], off
	v_lshl_add_u64 v[38:39], s[42:43], 0, v[156:157]
	s_mov_b32 m0, s78
	s_nop 0
	global_load_lds_dwordx4 v[38:39], off
	s_waitcnt vmcnt(8)
	s_waitcnt lgkmcnt(0)
	s_barrier
	s_setprio 1
	s_waitcnt lgkmcnt(0)
	v_mfma_f32_16x16x32_bf16 v[132:135], v[136:139], v[202:205], v[132:135]
	v_mfma_f32_16x16x32_bf16 v[132:135], v[140:143], v[206:209], v[132:135]
	v_mfma_f32_16x16x32_bf16 v[128:131], v[144:147], v[202:205], v[128:131]
	v_mfma_f32_16x16x32_bf16 v[128:131], v[148:151], v[206:209], v[128:131]
	v_mfma_f32_16x16x32_bf16 v[116:119], v[136:139], v[210:213], v[116:119]
	v_mfma_f32_16x16x32_bf16 v[116:119], v[140:143], v[214:217], v[116:119]
	v_mfma_f32_16x16x32_bf16 v[112:115], v[144:147], v[210:213], v[112:115]
	v_mfma_f32_16x16x32_bf16 v[112:115], v[148:151], v[214:217], v[112:115]
	v_mfma_f32_16x16x32_bf16 v[100:103], v[136:139], v[218:221], v[100:103]
	v_mfma_f32_16x16x32_bf16 v[100:103], v[140:143], v[222:225], v[100:103]
	v_mfma_f32_16x16x32_bf16 v[96:99], v[144:147], v[218:221], v[96:99]
	v_mfma_f32_16x16x32_bf16 v[96:99], v[148:151], v[222:225], v[96:99]
	v_mfma_f32_16x16x32_bf16 v[84:87], v[136:139], v[226:229], v[84:87]
	v_mfma_f32_16x16x32_bf16 v[84:87], v[140:143], v[240:243], v[84:87]
	v_mfma_f32_16x16x32_bf16 v[80:83], v[144:147], v[226:229], v[80:83]
	v_mfma_f32_16x16x32_bf16 v[80:83], v[148:151], v[240:243], v[80:83]
	s_setprio 0
	s_setprio 1
	v_mfma_f32_16x16x32_bf16 v[124:127], v[166:169], v[202:205], v[124:127]
	v_mfma_f32_16x16x32_bf16 v[124:127], v[170:173], v[206:209], v[124:127]
	v_mfma_f32_16x16x32_bf16 v[120:123], v[174:177], v[202:205], v[120:123]
	v_mfma_f32_16x16x32_bf16 v[120:123], v[198:201], v[206:209], v[120:123]
	v_mfma_f32_16x16x32_bf16 v[108:111], v[166:169], v[210:213], v[108:111]
	v_mfma_f32_16x16x32_bf16 v[108:111], v[170:173], v[214:217], v[108:111]
	v_mfma_f32_16x16x32_bf16 v[104:107], v[174:177], v[210:213], v[104:107]
	v_mfma_f32_16x16x32_bf16 v[104:107], v[198:201], v[214:217], v[104:107]
	v_mfma_f32_16x16x32_bf16 v[92:95], v[166:169], v[218:221], v[92:95]
	v_mfma_f32_16x16x32_bf16 v[92:95], v[170:173], v[222:225], v[92:95]
	v_mfma_f32_16x16x32_bf16 v[88:91], v[174:177], v[218:221], v[88:91]
	v_mfma_f32_16x16x32_bf16 v[88:91], v[198:201], v[222:225], v[88:91]
	v_mfma_f32_16x16x32_bf16 v[76:79], v[166:169], v[226:229], v[76:79]
	v_mfma_f32_16x16x32_bf16 v[76:79], v[170:173], v[240:243], v[76:79]
	v_mfma_f32_16x16x32_bf16 v[72:75], v[174:177], v[226:229], v[72:75]
	v_mfma_f32_16x16x32_bf16 v[72:75], v[198:201], v[240:243], v[72:75]
	s_setprio 0
	s_barrier
; #define PG8_STAGE(bufoff, gbase, voff) do { _Pragma("unroll") for (int _i = 0; _i < 2; ++_i) \
;         __builtin_amdgcn_global_load_lds((const unsigned*)((const char*)(gbase) + (voff)[_i]), (PG8_LAS unsigned*)(lds + (bufoff) + ldsw + _i * 8192), 16, 0, 0); } while (0)
; #define PG8_LDA(dst, b, h) do { _Pragma("unroll") for (int m = 0; m < 4; ++m) _Pragma("unroll") for (int k = 0; k < 2; ++k) dst[m][k] = *(const PG8_LAS bf16x8*)(lds + PG8_SA(b, h) + aoff + m * 2048 + k * 1024); } while (0)
; #define PG8_MMA(ai, bj, At, Bt) do { __builtin_amdgcn_s_setprio(1); _Pragma("unroll") for (int m = 0; m < 4; ++m) _Pragma("unroll") for (int n = 0; n < 2; ++n) _Pragma("unroll") for (int k = 0; k < 2; ++k) \
;         acc[ai][bj][m][n] = __builtin_amdgcn_mfma_f32_16x16x32_bf16(Bt[n][k], At[m][k], acc[ai][bj][m][n], 0, 0, 0); __builtin_amdgcn_s_setprio(0); } while (0)
; #define PG8_WAIT_V(n) asm volatile("s_waitcnt vmcnt(" #n ")" ::: "memory")
; #define PG8_WAIT_L(n) asm volatile("s_waitcnt lgkmcnt(" #n ")" ::: "memory")
; #define PG8_BAR __builtin_amdgcn_s_barrier()
; #define PG8_SCHED __builtin_amdgcn_sched_barrier(0)
;     ...
;         for (int t = 0; t < nt; t += 2) {
;             const bool last = (t == nt - 2);
;             const char* a1 = cA + (size_t)(t + 1) * kstep;
;             const char* a2 = last ? nA : cA + (size_t)(t + 2) * kstep; const char* b2 = last ? nB : cB + (size_t)(t + 2) * kstep;
;     ...
;             PG8_LDA(At, 1, 1); PG8_STAGE(PG8_SB(1, 0), b3, voffB); PG8_STAGE(PG8_SB(1, 1), b3 + hstep, voffB); PG8_STAGE(PG8_SA(1, 0), a3, voffA);
;             PG8_WAIT_V(8); PG8_WAIT_L(0); PG8_BAR; PG8_MMA(1, 0, At, B0); PG8_MMA(1, 1, At, B1); PG8_BAR; PG8_SCHED;
	s_add_i32 s42, s46, s41
	v_lshl_add_u64 v[38:39], v[178:179], 0, s[64:65]
	s_mov_b32 m0, s42
	ds_read_b128 v[202:205], v196 offset:49152
	ds_read_b128 v[206:209], v196 offset:50176
	ds_read_b128 v[210:213], v196 offset:51200
	ds_read_b128 v[214:217], v196 offset:52224
	ds_read_b128 v[218:221], v196 offset:53248
	ds_read_b128 v[222:225], v196 offset:54272
	ds_read_b128 v[226:229], v196 offset:55296
	ds_read_b128 v[240:243], v196 offset:56320
	global_load_lds_dwordx4 v[38:39], off
	s_add_i32 m0, s42, 0x2000
	s_add_u32 s28, s28, 0x80080
	v_lshl_add_u64 v[38:39], v[186:187], 0, s[64:65]
	s_addc_u32 s29, s29, 0
	s_add_i32 s42, s47, s41
	global_load_lds_dwordx4 v[38:39], off
	v_lshl_add_u64 v[38:39], s[28:29], 0, v[154:155]
	s_mov_b32 m0, s42
	s_nop 0
	global_load_lds_dwordx4 v[38:39], off
	v_lshl_add_u64 v[38:39], s[28:29], 0, v[158:159]
	s_add_i32 m0, s42, 0x2000
	s_nop 0
	global_load_lds_dwordx4 v[38:39], off
	v_lshl_add_u64 v[38:39], v[188:189], 0, s[64:65]
	s_mov_b32 m0, s79
	s_nop 0
	global_load_lds_dwordx4 v[38:39], off
	v_lshl_add_u64 v[38:39], v[190:191], 0, s[64:65]
	s_mov_b32 m0, s4
	s_nop 0
	global_load_lds_dwordx4 v[38:39], off
	s_waitcnt vmcnt(8)
	s_waitcnt lgkmcnt(0)
	s_barrier
	s_setprio 1
	s_waitcnt lgkmcnt(0)
	v_mfma_f32_16x16x32_bf16 v[68:71], v[136:139], v[202:205], v[68:71]
	v_mfma_f32_16x16x32_bf16 v[68:71], v[140:143], v[206:209], v[68:71]
	v_mfma_f32_16x16x32_bf16 v[64:67], v[144:147], v[202:205], v[64:67]
	v_mfma_f32_16x16x32_bf16 v[64:67], v[148:151], v[206:209], v[64:67]
	v_mfma_f32_16x16x32_bf16 v[52:55], v[136:139], v[210:213], v[52:55]
	v_mfma_f32_16x16x32_bf16 v[52:55], v[140:143], v[214:217], v[52:55]
	v_mfma_f32_16x16x32_bf16 v[48:51], v[144:147], v[210:213], v[48:51]
	v_mfma_f32_16x16x32_bf16 v[48:51], v[148:151], v[214:217], v[48:51]
	v_mfma_f32_16x16x32_bf16 v[34:37], v[136:139], v[218:221], v[34:37]
	v_mfma_f32_16x16x32_bf16 v[36:39], v[140:143], v[222:225], v[34:37]
	v_mfma_f32_16x16x32_bf16 v[26:29], v[144:147], v[218:221], v[26:29]
	v_mfma_f32_16x16x32_bf16 v[26:29], v[148:151], v[222:225], v[26:29]
	v_mfma_f32_16x16x32_bf16 v[14:17], v[136:139], v[226:229], v[14:17]
	v_mfma_f32_16x16x32_bf16 v[14:17], v[140:143], v[240:243], v[14:17]
	v_mfma_f32_16x16x32_bf16 v[10:13], v[144:147], v[226:229], v[10:13]
	v_mfma_f32_16x16x32_bf16 v[10:13], v[148:151], v[240:243], v[10:13]
	s_setprio 0
	s_setprio 1
	v_mfma_f32_16x16x32_bf16 v[60:63], v[166:169], v[202:205], v[60:63]
	v_mfma_f32_16x16x32_bf16 v[60:63], v[170:173], v[206:209], v[60:63]
	v_mfma_f32_16x16x32_bf16 v[56:59], v[174:177], v[202:205], v[56:59]
	v_mfma_f32_16x16x32_bf16 v[56:59], v[198:201], v[206:209], v[56:59]
	v_mfma_f32_16x16x32_bf16 v[44:47], v[166:169], v[210:213], v[44:47]
	v_mfma_f32_16x16x32_bf16 v[44:47], v[170:173], v[214:217], v[44:47]
	v_mfma_f32_16x16x32_bf16 v[40:43], v[174:177], v[210:213], v[40:43]
	v_mfma_f32_16x16x32_bf16 v[40:43], v[198:201], v[214:217], v[40:43]
	v_mfma_f32_16x16x32_bf16 v[22:25], v[166:169], v[218:221], v[22:25]
	v_mfma_f32_16x16x32_bf16 v[22:25], v[170:173], v[222:225], v[22:25]
	v_mfma_f32_16x16x32_bf16 v[18:21], v[174:177], v[218:221], v[18:21]
	v_mfma_f32_16x16x32_bf16 v[18:21], v[198:201], v[222:225], v[18:21]
	v_mfma_f32_16x16x32_bf16 v[6:9], v[166:169], v[226:229], v[6:9]
	v_mfma_f32_16x16x32_bf16 v[6:9], v[170:173], v[240:243], v[6:9]
	v_mfma_f32_16x16x32_bf16 v[2:5], v[174:177], v[226:229], v[2:5]
	v_mfma_f32_16x16x32_bf16 v[2:5], v[198:201], v[240:243], v[2:5]
	s_setprio 0
	s_barrier
	s_add_i32 s93, s93, 2
	s_add_u32 s30, s30, 0x100
	s_addc_u32 s31, s31, 0
	s_add_u32 s48, s48, 0x100
	s_addc_u32 s50, s50, 0
	s_cmp_gt_u32 s93, 29
	s_cbranch_scc0 .LBB0_407
	s_and_b64 vcc, exec, s[60:61]
	s_cbranch_vccz .LBB0_410
	s_barrier

; #define PG8_STAGE(bufoff, gbase, voff) do { _Pragma("unroll") for (int _i = 0; _i < 2; ++_i) \
;         __builtin_amdgcn_global_load_lds((const unsigned*)((const char*)(gbase) + (voff)[_i]), (PG8_LAS unsigned*)(lds + (bufoff) + ldsw + _i * 8192), 16, 0, 0); } while (0)
; #define PG8_LDA(dst, b, h) do { _Pragma("unroll") for (int m = 0; m < 4; ++m) _Pragma("unroll") for (int k = 0; k < 2; ++k) dst[m][k] = *(const PG8_LAS bf16x8*)(lds + PG8_SA(b, h) + aoff + m * 2048 + k * 1024); } while (0)
; #define PG8_LDB(dst, b, h) do { _Pragma("unroll") for (int n = 0; n < 2; ++n) _Pragma("unroll") for (int k = 0; k < 2; ++k) dst[n][k] = *(const PG8_LAS bf16x8*)(lds + PG8_SB(b, h) + boff + n * 2048 + k * 1024); } while (0)
; #define PG8_MMA(ai, bj, At, Bt) do { __builtin_amdgcn_s_setprio(1); _Pragma("unroll") for (int m = 0; m < 4; ++m) _Pragma("unroll") for (int n = 0; n < 2; ++n) _Pragma("unroll") for (int k = 0; k < 2; ++k) \
;         acc[ai][bj][m][n] = __builtin_amdgcn_mfma_f32_16x16x32_bf16(Bt[n][k], At[m][k], acc[ai][bj][m][n], 0, 0, 0); __builtin_amdgcn_s_setprio(0); } while (0)
; #define PG8_WAIT_V(n) asm volatile("s_waitcnt vmcnt(" #n ")" ::: "memory")
; #define PG8_WAIT_L(n) asm volatile("s_waitcnt lgkmcnt(" #n ")" ::: "memory")
; #define PG8_BAR __builtin_amdgcn_s_barrier()
; #define PG8_SCHED __builtin_amdgcn_sched_barrier(0)
;     ...
;             const bool last = (t == nt - 2);
;             const char* a1 = cA + (size_t)(t + 1) * kstep;
;             const char* a2 = last ? nA : cA + (size_t)(t + 2) * kstep; const char* b2 = last ? nB : cB + (size_t)(t + 2) * kstep;
;             const char* a3 = a2 + kstep; const char* b3 = b2 + kstep;
;             if (last && has_next) S.a_ready(nxt);
;             if constexpr (SP2) {
;             PG8_LDB(B0, 0, 0); PG8_LDB(B1, 0, 1); PG8_SCHED; PG8_LDA(At, 0, 0); PG8_STAGE(PG8_SA(1, 1), a1 + hstepA, voffA);
;             PG8_WAIT_V(8); PG8_WAIT_L(0); PG8_BAR; PG8_MMA(0, 0, At, B0); PG8_MMA(0, 1, At, B1); PG8_BAR; PG8_SCHED;
;             PG8_LDA(At, 0, 1); PG8_STAGE(PG8_SB(0, 0), b2, voffB); PG8_STAGE(PG8_SB(0, 1), b2 + hstep, voffB); PG8_STAGE(PG8_SA(0, 0), a2, voffA);
;             PG8_WAIT_V(8); PG8_WAIT_L(0); PG8_BAR; PG8_MMA(1, 0, At, B0); PG8_MMA(1, 1, At, B1); PG8_BAR; PG8_SCHED;
.LBB0_748:
	s_add_u32 s4, s18, 0x100
	s_addc_u32 s5, s19, 0
	s_add_i32 s42, 0, 0x10000
	s_cmp_eq_u32 s78, 4
	s_cselect_b32 s27, s13, s5
	s_cselect_b32 s26, s12, s4
	v_add_u32_e32 v153, s42, v150
	s_cselect_b32 s25, s11, s74
	s_cselect_b32 s24, s33, s48
	s_add_i32 s43, 0, 0x14000
	ds_read_b128 v[142:145], v153
	ds_read_b128 v[146:149], v153 offset:1024
	ds_read_b128 v[154:157], v153 offset:2048
	ds_read_b128 v[158:161], v153 offset:3072
	v_add_u32_e32 v153, s43, v150
	ds_read_b128 v[162:165], v153
	ds_read_b128 v[166:169], v153 offset:1024
	ds_read_b128 v[170:173], v153 offset:2048
	ds_read_b128 v[174:177], v153 offset:3072
	v_lshl_add_u64 v[182:183], s[18:19], 0, v[138:139]
	s_add_i32 m0, s17, 0xc000
	ds_read_b128 v[178:181], v152
	ds_read_b128 v[196:199], v152 offset:1024
	ds_read_b128 v[200:203], v152 offset:2048
	ds_read_b128 v[204:207], v152 offset:3072
	ds_read_b128 v[208:211], v152 offset:4096
	ds_read_b128 v[212:215], v152 offset:5120
	ds_read_b128 v[216:219], v152 offset:6144
	ds_read_b128 v[220:223], v152 offset:7168
	global_load_lds_dwordx4 v[182:183], off
	v_lshl_add_u64 v[182:183], s[18:19], 0, v[140:141]
	s_add_i32 m0, s17, 0xe000
	s_nop 0
	global_load_lds_dwordx4 v[182:183], off
	s_waitcnt vmcnt(8)
	s_waitcnt lgkmcnt(0)
	s_barrier
	s_setprio 1
	s_waitcnt lgkmcnt(0)
	v_mfma_f32_16x16x32_bf16 v[130:133], v[142:145], v[178:181], v[130:133]
	v_mfma_f32_16x16x32_bf16 v[130:133], v[146:149], v[196:199], v[130:133]
	v_mfma_f32_16x16x32_bf16 v[126:129], v[154:157], v[178:181], v[126:129]
	v_mfma_f32_16x16x32_bf16 v[126:129], v[158:161], v[196:199], v[126:129]
	v_mfma_f32_16x16x32_bf16 v[114:117], v[142:145], v[200:203], v[114:117]
	v_mfma_f32_16x16x32_bf16 v[114:117], v[146:149], v[204:207], v[114:117]
	v_mfma_f32_16x16x32_bf16 v[110:113], v[154:157], v[200:203], v[110:113]
	v_mfma_f32_16x16x32_bf16 v[110:113], v[158:161], v[204:207], v[110:113]
	v_mfma_f32_16x16x32_bf16 v[98:101], v[142:145], v[208:211], v[98:101]
	v_mfma_f32_16x16x32_bf16 v[98:101], v[146:149], v[212:215], v[98:101]
	v_mfma_f32_16x16x32_bf16 v[94:97], v[154:157], v[208:211], v[94:97]
	v_mfma_f32_16x16x32_bf16 v[94:97], v[158:161], v[212:215], v[94:97]
	v_mfma_f32_16x16x32_bf16 v[82:85], v[142:145], v[216:219], v[82:85]
	v_mfma_f32_16x16x32_bf16 v[82:85], v[146:149], v[220:223], v[82:85]
	v_mfma_f32_16x16x32_bf16 v[78:81], v[154:157], v[216:219], v[78:81]
	v_mfma_f32_16x16x32_bf16 v[78:81], v[158:161], v[220:223], v[78:81]
	s_setprio 0
	s_setprio 1
	v_mfma_f32_16x16x32_bf16 v[122:125], v[162:165], v[178:181], v[122:125]
	v_mfma_f32_16x16x32_bf16 v[122:125], v[166:169], v[196:199], v[122:125]
	v_mfma_f32_16x16x32_bf16 v[118:121], v[170:173], v[178:181], v[118:121]
	v_mfma_f32_16x16x32_bf16 v[118:121], v[174:177], v[196:199], v[118:121]
	v_mfma_f32_16x16x32_bf16 v[106:109], v[162:165], v[200:203], v[106:109]
	v_mfma_f32_16x16x32_bf16 v[106:109], v[166:169], v[204:207], v[106:109]
	v_mfma_f32_16x16x32_bf16 v[102:105], v[170:173], v[200:203], v[102:105]
	v_mfma_f32_16x16x32_bf16 v[102:105], v[174:177], v[204:207], v[102:105]
	v_mfma_f32_16x16x32_bf16 v[90:93], v[162:165], v[208:211], v[90:93]
	v_mfma_f32_16x16x32_bf16 v[90:93], v[166:169], v[212:215], v[90:93]
	v_mfma_f32_16x16x32_bf16 v[86:89], v[170:173], v[208:211], v[86:89]
	v_mfma_f32_16x16x32_bf16 v[86:89], v[174:177], v[212:215], v[86:89]
	v_mfma_f32_16x16x32_bf16 v[74:77], v[162:165], v[216:219], v[74:77]
	v_mfma_f32_16x16x32_bf16 v[74:77], v[166:169], v[220:223], v[74:77]
	v_mfma_f32_16x16x32_bf16 v[70:73], v[170:173], v[216:219], v[70:73]
	v_mfma_f32_16x16x32_bf16 v[70:73], v[174:177], v[220:223], v[70:73]
	s_setprio 0
	s_barrier
	s_add_i32 s18, s42, s30
	v_lshl_add_u64 v[182:183], s[24:25], 0, v[32:33]
	s_mov_b32 m0, s18
	ds_read_b128 v[178:181], v152 offset:16384
	ds_read_b128 v[196:199], v152 offset:17408
	ds_read_b128 v[200:203], v152 offset:18432
	ds_read_b128 v[204:207], v152 offset:19456
	ds_read_b128 v[208:211], v152 offset:20480
	ds_read_b128 v[212:215], v152 offset:21504
	ds_read_b128 v[216:219], v152 offset:22528
	ds_read_b128 v[220:223], v152 offset:23552
	global_load_lds_dwordx4 v[182:183], off
	s_add_i32 m0, s18, 0x2000
	s_add_u32 s18, s24, 0x20000
	v_lshl_add_u64 v[186:187], s[24:25], 0, v[136:137]
	s_addc_u32 s19, s25, 0
	s_add_i32 s42, s43, s30
	global_load_lds_dwordx4 v[186:187], off
	v_lshl_add_u64 v[188:189], s[18:19], 0, v[32:33]
	s_mov_b32 m0, s42
	v_lshl_add_u64 v[190:191], s[26:27], 0, v[134:135]
	global_load_lds_dwordx4 v[188:189], off
	v_lshl_add_u64 v[188:189], s[18:19], 0, v[136:137]
	s_add_i32 m0, s42, 0x2000
	s_nop 0
	global_load_lds_dwordx4 v[188:189], off
	v_lshl_add_u64 v[188:189], s[26:27], 0, v[30:31]
	s_mov_b32 m0, s17
	s_nop 0
	global_load_lds_dwordx4 v[188:189], off
	s_mov_b32 m0, s31
	s_nop 0
	global_load_lds_dwordx4 v[190:191], off
	s_waitcnt vmcnt(8)
	s_waitcnt lgkmcnt(0)
	s_barrier
; #define PG8_STAGE(bufoff, gbase, voff) do { _Pragma("unroll") for (int _i = 0; _i < 2; ++_i) \
;         __builtin_amdgcn_global_load_lds((const unsigned*)((const char*)(gbase) + (voff)[_i]), (PG8_LAS unsigned*)(lds + (bufoff) + ldsw + _i * 8192), 16, 0, 0); } while (0)
; #define PG8_LDA(dst, b, h) do { _Pragma("unroll") for (int m = 0; m < 4; ++m) _Pragma("unroll") for (int k = 0; k < 2; ++k) dst[m][k] = *(const PG8_LAS bf16x8*)(lds + PG8_SA(b, h) + aoff + m * 2048 + k * 1024); } while (0)
; #define PG8_LDB(dst, b, h) do { _Pragma("unroll") for (int n = 0; n < 2; ++n) _Pragma("unroll") for (int k = 0; k < 2; ++k) dst[n][k] = *(const PG8_LAS bf16x8*)(lds + PG8_SB(b, h) + boff + n * 2048 + k * 1024); } while (0)
; #define PG8_MMA(ai, bj, At, Bt) do { __builtin_amdgcn_s_setprio(1); _Pragma("unroll") for (int m = 0; m < 4; ++m) _Pragma("unroll") for (int n = 0; n < 2; ++n) _Pragma("unroll") for (int k = 0; k < 2; ++k) \
;         acc[ai][bj][m][n] = __builtin_amdgcn_mfma_f32_16x16x32_bf16(Bt[n][k], At[m][k], acc[ai][bj][m][n], 0, 0, 0); __builtin_amdgcn_s_setprio(0); } while (0)
; #define PG8_WAIT_V(n) asm volatile("s_waitcnt vmcnt(" #n ")" ::: "memory")
; #define PG8_WAIT_L(n) asm volatile("s_waitcnt lgkmcnt(" #n ")" ::: "memory")
; #define PG8_BAR __builtin_amdgcn_s_barrier()
; #define PG8_SCHED __builtin_amdgcn_sched_barrier(0)
;     ...
;             PG8_WAIT_V(8); PG8_WAIT_L(0); PG8_BAR; PG8_MMA(1, 0, At, B0); PG8_MMA(1, 1, At, B1); PG8_BAR; PG8_SCHED;
;             PG8_LDB(B0, 1, 0); PG8_LDB(B1, 1, 1); PG8_SCHED; PG8_LDA(At, 1, 0); PG8_STAGE(PG8_SA(0, 1), a2 + hstepA, voffA);
;             PG8_WAIT_V(8); PG8_WAIT_L(0); PG8_BAR; PG8_MMA(0, 0, At, B0); PG8_MMA(0, 1, At, B1); PG8_BAR; PG8_SCHED;
	s_setprio 1
	s_waitcnt lgkmcnt(0)
	v_mfma_f32_16x16x32_bf16 v[66:69], v[142:145], v[178:181], v[66:69]
	v_mfma_f32_16x16x32_bf16 v[66:69], v[146:149], v[196:199], v[66:69]
	v_mfma_f32_16x16x32_bf16 v[62:65], v[154:157], v[178:181], v[62:65]
	v_mfma_f32_16x16x32_bf16 v[62:65], v[158:161], v[196:199], v[62:65]
	v_mfma_f32_16x16x32_bf16 v[50:53], v[142:145], v[200:203], v[50:53]
	v_mfma_f32_16x16x32_bf16 v[50:53], v[146:149], v[204:207], v[50:53]
	v_mfma_f32_16x16x32_bf16 v[46:49], v[154:157], v[200:203], v[46:49]
	v_mfma_f32_16x16x32_bf16 v[46:49], v[158:161], v[204:207], v[46:49]
	v_mfma_f32_16x16x32_bf16 v[34:37], v[142:145], v[208:211], v[34:37]
	v_mfma_f32_16x16x32_bf16 v[34:37], v[146:149], v[212:215], v[34:37]
	v_mfma_f32_16x16x32_bf16 v[26:29], v[154:157], v[208:211], v[26:29]
	v_mfma_f32_16x16x32_bf16 v[26:29], v[158:161], v[212:215], v[26:29]
	v_mfma_f32_16x16x32_bf16 v[14:17], v[142:145], v[216:219], v[14:17]
	v_mfma_f32_16x16x32_bf16 v[14:17], v[146:149], v[220:223], v[14:17]
	v_mfma_f32_16x16x32_bf16 v[10:13], v[154:157], v[216:219], v[10:13]
	v_mfma_f32_16x16x32_bf16 v[10:13], v[158:161], v[220:223], v[10:13]
	s_setprio 0
	s_setprio 1
	v_mfma_f32_16x16x32_bf16 v[58:61], v[162:165], v[178:181], v[58:61]
	v_mfma_f32_16x16x32_bf16 v[58:61], v[166:169], v[196:199], v[58:61]
	v_mfma_f32_16x16x32_bf16 v[54:57], v[170:173], v[178:181], v[54:57]
	v_mfma_f32_16x16x32_bf16 v[54:57], v[174:177], v[196:199], v[54:57]
	v_mfma_f32_16x16x32_bf16 v[42:45], v[162:165], v[200:203], v[42:45]
	v_mfma_f32_16x16x32_bf16 v[42:45], v[166:169], v[204:207], v[42:45]
	v_mfma_f32_16x16x32_bf16 v[38:41], v[170:173], v[200:203], v[38:41]
	v_mfma_f32_16x16x32_bf16 v[38:41], v[174:177], v[204:207], v[38:41]
	v_mfma_f32_16x16x32_bf16 v[22:25], v[162:165], v[208:211], v[22:25]
	v_mfma_f32_16x16x32_bf16 v[22:25], v[166:169], v[212:215], v[22:25]
	v_mfma_f32_16x16x32_bf16 v[18:21], v[170:173], v[208:211], v[18:21]
	v_mfma_f32_16x16x32_bf16 v[18:21], v[174:177], v[212:215], v[18:21]
	v_mfma_f32_16x16x32_bf16 v[6:9], v[162:165], v[216:219], v[6:9]
	v_mfma_f32_16x16x32_bf16 v[6:9], v[166:169], v[220:223], v[6:9]
	v_mfma_f32_16x16x32_bf16 v[2:5], v[170:173], v[216:219], v[2:5]
	v_mfma_f32_16x16x32_bf16 v[2:5], v[174:177], v[220:223], v[2:5]
	s_setprio 0
	s_barrier
	s_add_i32 s42, 0, 0x18000
	v_add_u32_e32 v153, s42, v150
	s_add_i32 s43, 0, 0x1c000
	ds_read_b128 v[142:145], v153
	ds_read_b128 v[146:149], v153 offset:1024
	ds_read_b128 v[154:157], v153 offset:2048
	ds_read_b128 v[158:161], v153 offset:3072
	v_add_u32_e32 v153, s43, v150
	ds_read_b128 v[162:165], v153
	ds_read_b128 v[166:169], v153 offset:1024
	ds_read_b128 v[170:173], v153 offset:2048
	ds_read_b128 v[174:177], v153 offset:3072
	s_add_u32 s18, s26, 0xf0000
	s_addc_u32 s19, s27, 0
	s_mov_b32 m0, s38
	v_lshl_add_u64 v[224:225], s[18:19], 0, v[30:31]
	ds_read_b128 v[178:181], v152 offset:32768
	ds_read_b128 v[196:199], v152 offset:33792
	ds_read_b128 v[200:203], v152 offset:34816
	ds_read_b128 v[204:207], v152 offset:35840
	ds_read_b128 v[208:211], v152 offset:36864
	ds_read_b128 v[212:215], v152 offset:37888
	ds_read_b128 v[216:219], v152 offset:38912
	ds_read_b128 v[220:223], v152 offset:39936
	global_load_lds_dwordx4 v[224:225], off
	v_lshl_add_u64 v[224:225], s[18:19], 0, v[134:135]
	s_mov_b32 m0, s39
	s_nop 0
	global_load_lds_dwordx4 v[224:225], off
	s_waitcnt vmcnt(8)
	s_waitcnt lgkmcnt(0)
	s_barrier
	s_setprio 1
	s_waitcnt lgkmcnt(0)
	v_mfma_f32_16x16x32_bf16 v[130:133], v[142:145], v[178:181], v[130:133]
	v_mfma_f32_16x16x32_bf16 v[130:133], v[146:149], v[196:199], v[130:133]
	v_mfma_f32_16x16x32_bf16 v[126:129], v[154:157], v[178:181], v[126:129]
	v_mfma_f32_16x16x32_bf16 v[126:129], v[158:161], v[196:199], v[126:129]
	v_mfma_f32_16x16x32_bf16 v[114:117], v[142:145], v[200:203], v[114:117]
	v_mfma_f32_16x16x32_bf16 v[114:117], v[146:149], v[204:207], v[114:117]
	v_mfma_f32_16x16x32_bf16 v[110:113], v[154:157], v[200:203], v[110:113]
	v_mfma_f32_16x16x32_bf16 v[110:113], v[158:161], v[204:207], v[110:113]
	v_mfma_f32_16x16x32_bf16 v[98:101], v[142:145], v[208:211], v[98:101]
	v_mfma_f32_16x16x32_bf16 v[98:101], v[146:149], v[212:215], v[98:101]
	v_mfma_f32_16x16x32_bf16 v[94:97], v[154:157], v[208:211], v[94:97]
	v_mfma_f32_16x16x32_bf16 v[94:97], v[158:161], v[212:215], v[94:97]
	v_mfma_f32_16x16x32_bf16 v[82:85], v[142:145], v[216:219], v[82:85]
	v_mfma_f32_16x16x32_bf16 v[82:85], v[146:149], v[220:223], v[82:85]
	v_mfma_f32_16x16x32_bf16 v[78:81], v[154:157], v[216:219], v[78:81]
	v_mfma_f32_16x16x32_bf16 v[78:81], v[158:161], v[220:223], v[78:81]
	s_setprio 0
	s_setprio 1
	v_mfma_f32_16x16x32_bf16 v[122:125], v[162:165], v[178:181], v[122:125]
	v_mfma_f32_16x16x32_bf16 v[122:125], v[166:169], v[196:199], v[122:125]
	v_mfma_f32_16x16x32_bf16 v[118:121], v[170:173], v[178:181], v[118:121]
	v_mfma_f32_16x16x32_bf16 v[118:121], v[174:177], v[196:199], v[118:121]
	v_mfma_f32_16x16x32_bf16 v[106:109], v[162:165], v[200:203], v[106:109]
	v_mfma_f32_16x16x32_bf16 v[106:109], v[166:169], v[204:207], v[106:109]
	v_mfma_f32_16x16x32_bf16 v[102:105], v[170:173], v[200:203], v[102:105]
	v_mfma_f32_16x16x32_bf16 v[102:105], v[174:177], v[204:207], v[102:105]
	v_mfma_f32_16x16x32_bf16 v[90:93], v[162:165], v[208:211], v[90:93]
	v_mfma_f32_16x16x32_bf16 v[90:93], v[166:169], v[212:215], v[90:93]
	v_mfma_f32_16x16x32_bf16 v[86:89], v[170:173], v[208:211], v[86:89]
	v_mfma_f32_16x16x32_bf16 v[86:89], v[174:177], v[212:215], v[86:89]
	v_mfma_f32_16x16x32_bf16 v[74:77], v[162:165], v[216:219], v[74:77]
	v_mfma_f32_16x16x32_bf16 v[74:77], v[166:169], v[220:223], v[74:77]
	v_mfma_f32_16x16x32_bf16 v[70:73], v[170:173], v[216:219], v[70:73]
	v_mfma_f32_16x16x32_bf16 v[70:73], v[174:177], v[220:223], v[70:73]
	s_setprio 0
	s_barrier
; #define PG8_STAGE(bufoff, gbase, voff) do { _Pragma("unroll") for (int _i = 0; _i < 2; ++_i) \
;         __builtin_amdgcn_global_load_lds((const unsigned*)((const char*)(gbase) + (voff)[_i]), (PG8_LAS unsigned*)(lds + (bufoff) + ldsw + _i * 8192), 16, 0, 0); } while (0)
; #define PG8_LDA(dst, b, h) do { _Pragma("unroll") for (int m = 0; m < 4; ++m) _Pragma("unroll") for (int k = 0; k < 2; ++k) dst[m][k] = *(const PG8_LAS bf16x8*)(lds + PG8_SA(b, h) + aoff + m * 2048 + k * 1024); } while (0)
; #define PG8_MMA(ai, bj, At, Bt) do { __builtin_amdgcn_s_setprio(1); _Pragma("unroll") for (int m = 0; m < 4; ++m) _Pragma("unroll") for (int n = 0; n < 2; ++n) _Pragma("unroll") for (int k = 0; k < 2; ++k) \
;         acc[ai][bj][m][n] = __builtin_amdgcn_mfma_f32_16x16x32_bf16(Bt[n][k], At[m][k], acc[ai][bj][m][n], 0, 0, 0); __builtin_amdgcn_s_setprio(0); } while (0)
; #define PG8_WAIT_V(n) asm volatile("s_waitcnt vmcnt(" #n ")" ::: "memory")
; #define PG8_WAIT_L(n) asm volatile("s_waitcnt lgkmcnt(" #n ")" ::: "memory")
; #define PG8_BAR __builtin_amdgcn_s_barrier()
; #define PG8_SCHED __builtin_amdgcn_sched_barrier(0)
;     ...
;         for (int t = 0; t < nt; t += 2) {
;             const bool last = (t == nt - 2);
;             const char* a1 = cA + (size_t)(t + 1) * kstep;
;             const char* a2 = last ? nA : cA + (size_t)(t + 2) * kstep; const char* b2 = last ? nB : cB + (size_t)(t + 2) * kstep;
;     ...
;             PG8_LDA(At, 1, 1); PG8_STAGE(PG8_SB(1, 0), b3, voffB); PG8_STAGE(PG8_SB(1, 1), b3 + hstep, voffB); PG8_STAGE(PG8_SA(1, 0), a3, voffA);
;             PG8_WAIT_V(8); PG8_WAIT_L(0); PG8_BAR; PG8_MMA(1, 0, At, B0); PG8_MMA(1, 1, At, B1); PG8_BAR; PG8_SCHED;
	s_add_i32 s18, s42, s30
	v_lshl_add_u64 v[182:183], v[182:183], 0, s[64:65]
	s_mov_b32 m0, s18
	ds_read_b128 v[178:181], v152 offset:49152
	ds_read_b128 v[196:199], v152 offset:50176
	ds_read_b128 v[200:203], v152 offset:51200
	ds_read_b128 v[204:207], v152 offset:52224
	ds_read_b128 v[208:211], v152 offset:53248
	ds_read_b128 v[212:215], v152 offset:54272
	ds_read_b128 v[216:219], v152 offset:55296
	ds_read_b128 v[220:223], v152 offset:56320
	global_load_lds_dwordx4 v[182:183], off
	s_add_i32 m0, s18, 0x2000
	s_add_u32 s18, s24, 0x20080
	v_lshl_add_u64 v[182:183], v[186:187], 0, s[64:65]
	s_addc_u32 s19, s25, 0
	s_add_i32 s24, s43, s30
	global_load_lds_dwordx4 v[182:183], off
	v_lshl_add_u64 v[182:183], s[18:19], 0, v[32:33]
	s_mov_b32 m0, s24
	s_nop 0
	global_load_lds_dwordx4 v[182:183], off
	v_lshl_add_u64 v[182:183], s[18:19], 0, v[136:137]
	s_add_i32 m0, s24, 0x2000
	s_nop 0
	global_load_lds_dwordx4 v[182:183], off
	v_lshl_add_u64 v[182:183], v[188:189], 0, s[64:65]
	s_mov_b32 m0, s40
	s_nop 0
	global_load_lds_dwordx4 v[182:183], off
	v_lshl_add_u64 v[182:183], v[190:191], 0, s[64:65]
	s_mov_b32 m0, s41
	s_nop 0
	global_load_lds_dwordx4 v[182:183], off
	s_waitcnt vmcnt(8)
	s_waitcnt lgkmcnt(0)
	s_barrier
	s_setprio 1
	s_waitcnt lgkmcnt(0)
	v_mfma_f32_16x16x32_bf16 v[66:69], v[142:145], v[178:181], v[66:69]
	v_mfma_f32_16x16x32_bf16 v[66:69], v[146:149], v[196:199], v[66:69]
	v_mfma_f32_16x16x32_bf16 v[62:65], v[154:157], v[178:181], v[62:65]
	v_mfma_f32_16x16x32_bf16 v[62:65], v[158:161], v[196:199], v[62:65]
	v_mfma_f32_16x16x32_bf16 v[50:53], v[142:145], v[200:203], v[50:53]
	v_mfma_f32_16x16x32_bf16 v[50:53], v[146:149], v[204:207], v[50:53]
	v_mfma_f32_16x16x32_bf16 v[46:49], v[154:157], v[200:203], v[46:49]
	v_mfma_f32_16x16x32_bf16 v[46:49], v[158:161], v[204:207], v[46:49]
	v_mfma_f32_16x16x32_bf16 v[34:37], v[142:145], v[208:211], v[34:37]
	v_mfma_f32_16x16x32_bf16 v[34:37], v[146:149], v[212:215], v[34:37]
	v_mfma_f32_16x16x32_bf16 v[26:29], v[154:157], v[208:211], v[26:29]
	v_mfma_f32_16x16x32_bf16 v[26:29], v[158:161], v[212:215], v[26:29]
	v_mfma_f32_16x16x32_bf16 v[14:17], v[142:145], v[216:219], v[14:17]
	v_mfma_f32_16x16x32_bf16 v[14:17], v[146:149], v[220:223], v[14:17]
	v_mfma_f32_16x16x32_bf16 v[10:13], v[154:157], v[216:219], v[10:13]
	v_mfma_f32_16x16x32_bf16 v[10:13], v[158:161], v[220:223], v[10:13]
	s_setprio 0
	s_setprio 1
	v_mfma_f32_16x16x32_bf16 v[58:61], v[162:165], v[178:181], v[58:61]
	v_mfma_f32_16x16x32_bf16 v[58:61], v[166:169], v[196:199], v[58:61]
	v_mfma_f32_16x16x32_bf16 v[54:57], v[170:173], v[178:181], v[54:57]
	v_mfma_f32_16x16x32_bf16 v[54:57], v[174:177], v[196:199], v[54:57]
	v_mfma_f32_16x16x32_bf16 v[42:45], v[162:165], v[200:203], v[42:45]
	v_mfma_f32_16x16x32_bf16 v[42:45], v[166:169], v[204:207], v[42:45]
	v_mfma_f32_16x16x32_bf16 v[38:41], v[170:173], v[200:203], v[38:41]
	v_mfma_f32_16x16x32_bf16 v[38:41], v[174:177], v[204:207], v[38:41]
	v_mfma_f32_16x16x32_bf16 v[22:25], v[162:165], v[208:211], v[22:25]
	v_mfma_f32_16x16x32_bf16 v[22:25], v[166:169], v[212:215], v[22:25]
	v_mfma_f32_16x16x32_bf16 v[18:21], v[170:173], v[208:211], v[18:21]
	v_mfma_f32_16x16x32_bf16 v[18:21], v[174:177], v[212:215], v[18:21]
	v_mfma_f32_16x16x32_bf16 v[6:9], v[162:165], v[216:219], v[6:9]
	v_mfma_f32_16x16x32_bf16 v[6:9], v[166:169], v[220:223], v[6:9]
	v_mfma_f32_16x16x32_bf16 v[2:5], v[170:173], v[216:219], v[2:5]
	v_mfma_f32_16x16x32_bf16 v[2:5], v[174:177], v[220:223], v[2:5]
	s_setprio 0
	s_barrier
	s_add_i32 s78, s78, 2
	s_add_u32 s48, s48, 0x100
	s_addc_u32 s74, s74, 0
	s_cmp_gt_u32 s78, 5
	s_mov_b64 s[18:19], s[4:5]
	s_cbranch_scc0 .LBB0_748
	s_and_b64 vcc, exec, s[8:9]
	s_cbranch_vccz .LBB0_751
	s_barrier

; #define PG8_STAGE(bufoff, gbase, voff) do { _Pragma("unroll") for (int _i = 0; _i < 2; ++_i) \
;         __builtin_amdgcn_global_load_lds((const unsigned*)((const char*)(gbase) + (voff)[_i]), (PG8_LAS unsigned*)(lds + (bufoff) + ldsw + _i * 8192), 16, 0, 0); } while (0)
; #define PG8_LDA(dst, b, h) do { _Pragma("unroll") for (int m = 0; m < 4; ++m) _Pragma("unroll") for (int k = 0; k < 2; ++k) dst[m][k] = *(const PG8_LAS bf16x8*)(lds + PG8_SA(b, h) + aoff + m * 2048 + k * 1024); } while (0)
; #define PG8_LDB(dst, b, h) do { _Pragma("unroll") for (int n = 0; n < 2; ++n) _Pragma("unroll") for (int k = 0; k < 2; ++k) dst[n][k] = *(const PG8_LAS bf16x8*)(lds + PG8_SB(b, h) + boff + n * 2048 + k * 1024); } while (0)
; #define PG8_MMA(ai, bj, At, Bt) do { __builtin_amdgcn_s_setprio(1); _Pragma("unroll") for (int m = 0; m < 4; ++m) _Pragma("unroll") for (int n = 0; n < 2; ++n) _Pragma("unroll") for (int k = 0; k < 2; ++k) \
;         acc[ai][bj][m][n] = __builtin_amdgcn_mfma_f32_16x16x32_bf16(Bt[n][k], At[m][k], acc[ai][bj][m][n], 0, 0, 0); __builtin_amdgcn_s_setprio(0); } while (0)
; #define PG8_WAIT_V(n) asm volatile("s_waitcnt vmcnt(" #n ")" ::: "memory")
; #define PG8_WAIT_L(n) asm volatile("s_waitcnt lgkmcnt(" #n ")" ::: "memory")
; #define PG8_BAR __builtin_amdgcn_s_barrier()
; #define PG8_SCHED __builtin_amdgcn_sched_barrier(0)
;     ...
;             const bool last = (t == nt - 2);
;             const char* a1 = cA + (size_t)(t + 1) * kstep;
;             const char* a2 = last ? nA : cA + (size_t)(t + 2) * kstep; const char* b2 = last ? nB : cB + (size_t)(t + 2) * kstep;
;             const char* a3 = a2 + kstep; const char* b3 = b2 + kstep;
;             if (last && has_next) S.a_ready(nxt);
;             if constexpr (SP2) {
;             PG8_LDB(B0, 0, 0); PG8_LDB(B1, 0, 1); PG8_SCHED; PG8_LDA(At, 0, 0); PG8_STAGE(PG8_SA(1, 1), a1 + hstepA, voffA);
;             PG8_WAIT_V(8); PG8_WAIT_L(0); PG8_BAR; PG8_MMA(0, 0, At, B0); PG8_MMA(0, 1, At, B1); PG8_BAR; PG8_SCHED;
;             PG8_LDA(At, 0, 1); PG8_STAGE(PG8_SB(0, 0), b2, voffB); PG8_STAGE(PG8_SB(0, 1), b2 + hstep, voffB); PG8_STAGE(PG8_SA(0, 0), a2, voffA);
;             PG8_WAIT_V(8); PG8_WAIT_L(0); PG8_BAR; PG8_MMA(1, 0, At, B0); PG8_MMA(1, 1, At, B1); PG8_BAR; PG8_SCHED;
.LBB0_766:
	s_add_u32 s29, s24, s28
	s_addc_u32 s42, s25, 0
	s_add_u32 s30, s29, 0x100
	s_addc_u32 s31, s42, 0
	s_and_b64 s[6:7], s[26:27], exec
	s_cselect_b32 s31, s15, s31
	s_cselect_b32 s30, s14, s30
	s_add_u32 s6, s22, s28
	s_addc_u32 s7, s23, 0
	s_add_u32 s28, s6, 0x100
	s_addc_u32 s38, s7, 0
	s_add_i32 s46, 0, 0x10000
	s_and_b64 s[6:7], s[26:27], exec
	s_cselect_b32 s39, s13, s38
	s_cselect_b32 s38, s33, s28
	s_add_i32 s7, 0, 0x14000
	s_add_u32 s92, s29, 0xf0080
	s_addc_u32 s93, s42, 0
	s_add_i32 s42, s46, s53
	s_add_i32 m0, s19, 0xc000
	s_add_i32 s47, s19, 0xe000
	s_add_i32 s6, s42, 0x2000
	v_add_u32_e32 v149, s46, v146
	s_add_u32 s90, s38, 0x10000
	ds_read_b128 v[138:141], v149
	ds_read_b128 v[142:145], v149 offset:1024
	ds_read_b128 v[150:153], v149 offset:2048
	ds_read_b128 v[154:157], v149 offset:3072
	v_add_u32_e32 v149, s7, v146
	s_addc_u32 s91, s39, 0
	s_add_i32 s43, s7, s53
	ds_read_b128 v[158:161], v149
	ds_read_b128 v[162:165], v149 offset:1024
	ds_read_b128 v[166:169], v149 offset:2048
	ds_read_b128 v[170:173], v149 offset:3072
	s_add_i32 s75, s43, 0x2000
	s_add_i32 vcc_hi, 0, 0x18000
	s_add_i32 s49, 0, 0x1c000
	s_add_u32 s28, s30, 0xf0000
	s_addc_u32 s29, s31, 0
	s_add_i32 vcc_lo, vcc_hi, s53
	s_add_i32 s51, vcc_lo, 0x2000
	s_add_u32 s26, s38, 0x10080
	s_addc_u32 s27, s39, 0
	s_add_i32 s7, s49, s53
	s_add_i32 s46, s7, 0x2000
	v_lshl_add_u64 v[182:183], s[92:93], 0, v[136:137]
	ds_read_b128 v[174:177], v148
	ds_read_b128 v[178:181], v148 offset:1024
	ds_read_b128 v[196:199], v148 offset:2048
	ds_read_b128 v[200:203], v148 offset:3072
	ds_read_b128 v[204:207], v148 offset:4096
	ds_read_b128 v[208:211], v148 offset:5120
	ds_read_b128 v[212:215], v148 offset:6144
	ds_read_b128 v[216:219], v148 offset:7168
	global_load_lds_dwordx4 v[182:183], off
	v_lshl_add_u64 v[182:183], s[92:93], 0, v[134:135]
	s_mov_b32 m0, s47
	s_nop 0
	global_load_lds_dwordx4 v[182:183], off
	s_waitcnt vmcnt(8)
	s_waitcnt lgkmcnt(0)
	s_barrier
	s_setprio 1
	s_waitcnt lgkmcnt(0)
	v_mfma_f32_16x16x32_bf16 v[130:133], v[138:141], v[174:177], v[130:133]
	v_mfma_f32_16x16x32_bf16 v[130:133], v[142:145], v[178:181], v[130:133]
	v_mfma_f32_16x16x32_bf16 v[126:129], v[150:153], v[174:177], v[126:129]
	v_mfma_f32_16x16x32_bf16 v[126:129], v[154:157], v[178:181], v[126:129]
	v_mfma_f32_16x16x32_bf16 v[114:117], v[138:141], v[196:199], v[114:117]
	v_mfma_f32_16x16x32_bf16 v[114:117], v[142:145], v[200:203], v[114:117]
	v_mfma_f32_16x16x32_bf16 v[110:113], v[150:153], v[196:199], v[110:113]
	v_mfma_f32_16x16x32_bf16 v[110:113], v[154:157], v[200:203], v[110:113]
	v_mfma_f32_16x16x32_bf16 v[98:101], v[138:141], v[204:207], v[98:101]
	v_mfma_f32_16x16x32_bf16 v[98:101], v[142:145], v[208:211], v[98:101]
	v_mfma_f32_16x16x32_bf16 v[94:97], v[150:153], v[204:207], v[94:97]
	v_mfma_f32_16x16x32_bf16 v[94:97], v[154:157], v[208:211], v[94:97]
	v_mfma_f32_16x16x32_bf16 v[82:85], v[138:141], v[212:215], v[82:85]
	v_mfma_f32_16x16x32_bf16 v[82:85], v[142:145], v[216:219], v[82:85]
	v_mfma_f32_16x16x32_bf16 v[78:81], v[150:153], v[212:215], v[78:81]
	v_mfma_f32_16x16x32_bf16 v[78:81], v[154:157], v[216:219], v[78:81]
	s_setprio 0
	s_setprio 1
	v_mfma_f32_16x16x32_bf16 v[122:125], v[158:161], v[174:177], v[122:125]
	v_mfma_f32_16x16x32_bf16 v[122:125], v[162:165], v[178:181], v[122:125]
	v_mfma_f32_16x16x32_bf16 v[118:121], v[166:169], v[174:177], v[118:121]
	v_mfma_f32_16x16x32_bf16 v[118:121], v[170:173], v[178:181], v[118:121]
	v_mfma_f32_16x16x32_bf16 v[106:109], v[158:161], v[196:199], v[106:109]
	v_mfma_f32_16x16x32_bf16 v[106:109], v[162:165], v[200:203], v[106:109]
	v_mfma_f32_16x16x32_bf16 v[102:105], v[166:169], v[196:199], v[102:105]
	v_mfma_f32_16x16x32_bf16 v[102:105], v[170:173], v[200:203], v[102:105]
	v_mfma_f32_16x16x32_bf16 v[90:93], v[158:161], v[204:207], v[90:93]
	v_mfma_f32_16x16x32_bf16 v[90:93], v[162:165], v[208:211], v[90:93]
	v_mfma_f32_16x16x32_bf16 v[86:89], v[166:169], v[204:207], v[86:89]
	v_mfma_f32_16x16x32_bf16 v[86:89], v[170:173], v[208:211], v[86:89]
	v_mfma_f32_16x16x32_bf16 v[74:77], v[158:161], v[212:215], v[74:77]
	v_mfma_f32_16x16x32_bf16 v[74:77], v[162:165], v[216:219], v[74:77]
	v_mfma_f32_16x16x32_bf16 v[70:73], v[166:169], v[212:215], v[70:73]
	v_mfma_f32_16x16x32_bf16 v[70:73], v[170:173], v[216:219], v[70:73]
	s_setprio 0
	s_barrier
	s_mov_b32 m0, s42
	v_lshl_add_u64 v[182:183], s[38:39], 0, v[32:33]
	ds_read_b128 v[174:177], v148 offset:16384
	ds_read_b128 v[178:181], v148 offset:17408
	ds_read_b128 v[196:199], v148 offset:18432
	ds_read_b128 v[200:203], v148 offset:19456
	ds_read_b128 v[204:207], v148 offset:20480
	ds_read_b128 v[208:211], v148 offset:21504
	ds_read_b128 v[212:215], v148 offset:22528
	ds_read_b128 v[216:219], v148 offset:23552
	global_load_lds_dwordx4 v[182:183], off
	v_lshl_add_u64 v[186:187], s[38:39], 0, v[30:31]
	s_mov_b32 m0, s6
	v_lshl_add_u64 v[188:189], s[90:91], 0, v[32:33]
	global_load_lds_dwordx4 v[186:187], off
	s_mov_b32 m0, s43
	v_lshl_add_u64 v[190:191], s[30:31], 0, v[134:135]
	global_load_lds_dwordx4 v[188:189], off
	v_lshl_add_u64 v[188:189], s[90:91], 0, v[30:31]
	s_mov_b32 m0, s75
	s_nop 0
	global_load_lds_dwordx4 v[188:189], off
	v_lshl_add_u64 v[188:189], s[30:31], 0, v[136:137]
	s_mov_b32 m0, s19
	s_nop 0
	global_load_lds_dwordx4 v[188:189], off
	s_mov_b32 m0, s74
	s_nop 0
	global_load_lds_dwordx4 v[190:191], off
	s_waitcnt vmcnt(8)
	s_waitcnt lgkmcnt(0)
	s_barrier
; #define PG8_STAGE(bufoff, gbase, voff) do { _Pragma("unroll") for (int _i = 0; _i < 2; ++_i) \
;         __builtin_amdgcn_global_load_lds((const unsigned*)((const char*)(gbase) + (voff)[_i]), (PG8_LAS unsigned*)(lds + (bufoff) + ldsw + _i * 8192), 16, 0, 0); } while (0)
; #define PG8_LDA(dst, b, h) do { _Pragma("unroll") for (int m = 0; m < 4; ++m) _Pragma("unroll") for (int k = 0; k < 2; ++k) dst[m][k] = *(const PG8_LAS bf16x8*)(lds + PG8_SA(b, h) + aoff + m * 2048 + k * 1024); } while (0)
; #define PG8_LDB(dst, b, h) do { _Pragma("unroll") for (int n = 0; n < 2; ++n) _Pragma("unroll") for (int k = 0; k < 2; ++k) dst[n][k] = *(const PG8_LAS bf16x8*)(lds + PG8_SB(b, h) + boff + n * 2048 + k * 1024); } while (0)
; #define PG8_MMA(ai, bj, At, Bt) do { __builtin_amdgcn_s_setprio(1); _Pragma("unroll") for (int m = 0; m < 4; ++m) _Pragma("unroll") for (int n = 0; n < 2; ++n) _Pragma("unroll") for (int k = 0; k < 2; ++k) \
;         acc[ai][bj][m][n] = __builtin_amdgcn_mfma_f32_16x16x32_bf16(Bt[n][k], At[m][k], acc[ai][bj][m][n], 0, 0, 0); __builtin_amdgcn_s_setprio(0); } while (0)
; #define PG8_WAIT_V(n) asm volatile("s_waitcnt vmcnt(" #n ")" ::: "memory")
; #define PG8_WAIT_L(n) asm volatile("s_waitcnt lgkmcnt(" #n ")" ::: "memory")
; #define PG8_BAR __builtin_amdgcn_s_barrier()
; #define PG8_SCHED __builtin_amdgcn_sched_barrier(0)
;     ...
;             PG8_WAIT_V(8); PG8_WAIT_L(0); PG8_BAR; PG8_MMA(1, 0, At, B0); PG8_MMA(1, 1, At, B1); PG8_BAR; PG8_SCHED;
;             PG8_LDB(B0, 1, 0); PG8_LDB(B1, 1, 1); PG8_SCHED; PG8_LDA(At, 1, 0); PG8_STAGE(PG8_SA(0, 1), a2 + hstepA, voffA);
;             PG8_WAIT_V(8); PG8_WAIT_L(0); PG8_BAR; PG8_MMA(0, 0, At, B0); PG8_MMA(0, 1, At, B1); PG8_BAR; PG8_SCHED;
	s_setprio 1
	s_waitcnt lgkmcnt(0)
	v_mfma_f32_16x16x32_bf16 v[66:69], v[138:141], v[174:177], v[66:69]
	v_mfma_f32_16x16x32_bf16 v[66:69], v[142:145], v[178:181], v[66:69]
	v_mfma_f32_16x16x32_bf16 v[62:65], v[150:153], v[174:177], v[62:65]
	v_mfma_f32_16x16x32_bf16 v[62:65], v[154:157], v[178:181], v[62:65]
	v_mfma_f32_16x16x32_bf16 v[50:53], v[138:141], v[196:199], v[50:53]
	v_mfma_f32_16x16x32_bf16 v[50:53], v[142:145], v[200:203], v[50:53]
	v_mfma_f32_16x16x32_bf16 v[46:49], v[150:153], v[196:199], v[46:49]
	v_mfma_f32_16x16x32_bf16 v[46:49], v[154:157], v[200:203], v[46:49]
	v_mfma_f32_16x16x32_bf16 v[34:37], v[138:141], v[204:207], v[34:37]
	v_mfma_f32_16x16x32_bf16 v[34:37], v[142:145], v[208:211], v[34:37]
	v_mfma_f32_16x16x32_bf16 v[26:29], v[150:153], v[204:207], v[26:29]
	v_mfma_f32_16x16x32_bf16 v[26:29], v[154:157], v[208:211], v[26:29]
	v_mfma_f32_16x16x32_bf16 v[14:17], v[138:141], v[212:215], v[14:17]
	v_mfma_f32_16x16x32_bf16 v[14:17], v[142:145], v[216:219], v[14:17]
	v_mfma_f32_16x16x32_bf16 v[10:13], v[150:153], v[212:215], v[10:13]
	v_mfma_f32_16x16x32_bf16 v[10:13], v[154:157], v[216:219], v[10:13]
	s_setprio 0
	s_setprio 1
	v_mfma_f32_16x16x32_bf16 v[58:61], v[158:161], v[174:177], v[58:61]
	v_mfma_f32_16x16x32_bf16 v[58:61], v[162:165], v[178:181], v[58:61]
	v_mfma_f32_16x16x32_bf16 v[54:57], v[166:169], v[174:177], v[54:57]
	v_mfma_f32_16x16x32_bf16 v[54:57], v[170:173], v[178:181], v[54:57]
	v_mfma_f32_16x16x32_bf16 v[42:45], v[158:161], v[196:199], v[42:45]
	v_mfma_f32_16x16x32_bf16 v[42:45], v[162:165], v[200:203], v[42:45]
	v_mfma_f32_16x16x32_bf16 v[38:41], v[166:169], v[196:199], v[38:41]
	v_mfma_f32_16x16x32_bf16 v[38:41], v[170:173], v[200:203], v[38:41]
	v_mfma_f32_16x16x32_bf16 v[22:25], v[158:161], v[204:207], v[22:25]
	v_mfma_f32_16x16x32_bf16 v[22:25], v[162:165], v[208:211], v[22:25]
	v_mfma_f32_16x16x32_bf16 v[18:21], v[166:169], v[204:207], v[18:21]
	v_mfma_f32_16x16x32_bf16 v[18:21], v[170:173], v[208:211], v[18:21]
	v_mfma_f32_16x16x32_bf16 v[6:9], v[158:161], v[212:215], v[6:9]
	v_mfma_f32_16x16x32_bf16 v[6:9], v[162:165], v[216:219], v[6:9]
	v_mfma_f32_16x16x32_bf16 v[2:5], v[166:169], v[212:215], v[2:5]
	v_mfma_f32_16x16x32_bf16 v[2:5], v[170:173], v[216:219], v[2:5]
	s_setprio 0
	s_barrier
	v_add_u32_e32 v149, vcc_hi, v146
	ds_read_b128 v[138:141], v149
	ds_read_b128 v[142:145], v149 offset:1024
	ds_read_b128 v[150:153], v149 offset:2048
	ds_read_b128 v[154:157], v149 offset:3072
	v_add_u32_e32 v149, s49, v146
	ds_read_b128 v[158:161], v149
	ds_read_b128 v[162:165], v149 offset:1024
	ds_read_b128 v[166:169], v149 offset:2048
	ds_read_b128 v[170:173], v149 offset:3072
	s_mov_b32 m0, s78
	v_lshl_add_u64 v[220:221], s[28:29], 0, v[136:137]
	ds_read_b128 v[174:177], v148 offset:32768
	ds_read_b128 v[178:181], v148 offset:33792
	ds_read_b128 v[196:199], v148 offset:34816
	ds_read_b128 v[200:203], v148 offset:35840
	ds_read_b128 v[204:207], v148 offset:36864
	ds_read_b128 v[208:211], v148 offset:37888
	ds_read_b128 v[212:215], v148 offset:38912
	ds_read_b128 v[216:219], v148 offset:39936
	global_load_lds_dwordx4 v[220:221], off
	v_lshl_add_u64 v[220:221], s[28:29], 0, v[134:135]
	s_mov_b32 m0, s79
	s_nop 0
	global_load_lds_dwordx4 v[220:221], off
	s_waitcnt vmcnt(8)
	s_waitcnt lgkmcnt(0)
	s_barrier
	s_setprio 1
	s_waitcnt lgkmcnt(0)
	v_mfma_f32_16x16x32_bf16 v[130:133], v[138:141], v[174:177], v[130:133]
	v_mfma_f32_16x16x32_bf16 v[130:133], v[142:145], v[178:181], v[130:133]
	v_mfma_f32_16x16x32_bf16 v[126:129], v[150:153], v[174:177], v[126:129]
	v_mfma_f32_16x16x32_bf16 v[126:129], v[154:157], v[178:181], v[126:129]
	v_mfma_f32_16x16x32_bf16 v[114:117], v[138:141], v[196:199], v[114:117]
	v_mfma_f32_16x16x32_bf16 v[114:117], v[142:145], v[200:203], v[114:117]
	v_mfma_f32_16x16x32_bf16 v[110:113], v[150:153], v[196:199], v[110:113]
	v_mfma_f32_16x16x32_bf16 v[110:113], v[154:157], v[200:203], v[110:113]
	v_mfma_f32_16x16x32_bf16 v[98:101], v[138:141], v[204:207], v[98:101]
	v_mfma_f32_16x16x32_bf16 v[98:101], v[142:145], v[208:211], v[98:101]
	v_mfma_f32_16x16x32_bf16 v[94:97], v[150:153], v[204:207], v[94:97]
	v_mfma_f32_16x16x32_bf16 v[94:97], v[154:157], v[208:211], v[94:97]
	v_mfma_f32_16x16x32_bf16 v[82:85], v[138:141], v[212:215], v[82:85]
	v_mfma_f32_16x16x32_bf16 v[82:85], v[142:145], v[216:219], v[82:85]
	v_mfma_f32_16x16x32_bf16 v[78:81], v[150:153], v[212:215], v[78:81]
	v_mfma_f32_16x16x32_bf16 v[78:81], v[154:157], v[216:219], v[78:81]
	s_setprio 0
	s_setprio 1
	v_mfma_f32_16x16x32_bf16 v[122:125], v[158:161], v[174:177], v[122:125]
	v_mfma_f32_16x16x32_bf16 v[122:125], v[162:165], v[178:181], v[122:125]
	v_mfma_f32_16x16x32_bf16 v[118:121], v[166:169], v[174:177], v[118:121]
	v_mfma_f32_16x16x32_bf16 v[118:121], v[170:173], v[178:181], v[118:121]
	v_mfma_f32_16x16x32_bf16 v[106:109], v[158:161], v[196:199], v[106:109]
	v_mfma_f32_16x16x32_bf16 v[106:109], v[162:165], v[200:203], v[106:109]
	v_mfma_f32_16x16x32_bf16 v[102:105], v[166:169], v[196:199], v[102:105]
	v_mfma_f32_16x16x32_bf16 v[102:105], v[170:173], v[200:203], v[102:105]
	v_mfma_f32_16x16x32_bf16 v[90:93], v[158:161], v[204:207], v[90:93]
	v_mfma_f32_16x16x32_bf16 v[90:93], v[162:165], v[208:211], v[90:93]
	v_mfma_f32_16x16x32_bf16 v[86:89], v[166:169], v[204:207], v[86:89]
	v_mfma_f32_16x16x32_bf16 v[86:89], v[170:173], v[208:211], v[86:89]
	v_mfma_f32_16x16x32_bf16 v[74:77], v[158:161], v[212:215], v[74:77]
	v_mfma_f32_16x16x32_bf16 v[74:77], v[162:165], v[216:219], v[74:77]
	v_mfma_f32_16x16x32_bf16 v[70:73], v[166:169], v[212:215], v[70:73]
	v_mfma_f32_16x16x32_bf16 v[70:73], v[170:173], v[216:219], v[70:73]
	s_setprio 0
	s_barrier
; #define PG8_STAGE(bufoff, gbase, voff) do { _Pragma("unroll") for (int _i = 0; _i < 2; ++_i) \
;         __builtin_amdgcn_global_load_lds((const unsigned*)((const char*)(gbase) + (voff)[_i]), (PG8_LAS unsigned*)(lds + (bufoff) + ldsw + _i * 8192), 16, 0, 0); } while (0)
; #define PG8_LDA(dst, b, h) do { _Pragma("unroll") for (int m = 0; m < 4; ++m) _Pragma("unroll") for (int k = 0; k < 2; ++k) dst[m][k] = *(const PG8_LAS bf16x8*)(lds + PG8_SA(b, h) + aoff + m * 2048 + k * 1024); } while (0)
; #define PG8_MMA(ai, bj, At, Bt) do { __builtin_amdgcn_s_setprio(1); _Pragma("unroll") for (int m = 0; m < 4; ++m) _Pragma("unroll") for (int n = 0; n < 2; ++n) _Pragma("unroll") for (int k = 0; k < 2; ++k) \
;         acc[ai][bj][m][n] = __builtin_amdgcn_mfma_f32_16x16x32_bf16(Bt[n][k], At[m][k], acc[ai][bj][m][n], 0, 0, 0); __builtin_amdgcn_s_setprio(0); } while (0)
; #define PG8_WAIT_V(n) asm volatile("s_waitcnt vmcnt(" #n ")" ::: "memory")
; #define PG8_WAIT_L(n) asm volatile("s_waitcnt lgkmcnt(" #n ")" ::: "memory")
; #define PG8_BAR __builtin_amdgcn_s_barrier()
; #define PG8_SCHED __builtin_amdgcn_sched_barrier(0)
;     ...
;         for (int t = 0; t < nt; t += 2) {
;             const bool last = (t == nt - 2);
;             const char* a1 = cA + (size_t)(t + 1) * kstep;
;             const char* a2 = last ? nA : cA + (size_t)(t + 2) * kstep; const char* b2 = last ? nB : cB + (size_t)(t + 2) * kstep;
;     ...
;             PG8_LDA(At, 1, 1); PG8_STAGE(PG8_SB(1, 0), b3, voffB); PG8_STAGE(PG8_SB(1, 1), b3 + hstep, voffB); PG8_STAGE(PG8_SA(1, 0), a3, voffA);
;             PG8_WAIT_V(8); PG8_WAIT_L(0); PG8_BAR; PG8_MMA(1, 0, At, B0); PG8_MMA(1, 1, At, B1); PG8_BAR; PG8_SCHED;
	s_mov_b32 m0, vcc_lo
	v_lshl_add_u64 v[182:183], v[182:183], 0, s[64:65]
	ds_read_b128 v[174:177], v148 offset:49152
	ds_read_b128 v[178:181], v148 offset:50176
	ds_read_b128 v[196:199], v148 offset:51200
	ds_read_b128 v[200:203], v148 offset:52224
	ds_read_b128 v[204:207], v148 offset:53248
	ds_read_b128 v[208:211], v148 offset:54272
	ds_read_b128 v[212:215], v148 offset:55296
	ds_read_b128 v[216:219], v148 offset:56320
	global_load_lds_dwordx4 v[182:183], off
	v_lshl_add_u64 v[182:183], v[186:187], 0, s[64:65]
	s_mov_b32 m0, s51
	s_nop 0
	global_load_lds_dwordx4 v[182:183], off
	v_lshl_add_u64 v[182:183], s[26:27], 0, v[32:33]
	s_mov_b32 m0, s7
	s_nop 0
	global_load_lds_dwordx4 v[182:183], off
	v_lshl_add_u64 v[182:183], s[26:27], 0, v[30:31]
	s_mov_b32 m0, s46
	s_nop 0
	global_load_lds_dwordx4 v[182:183], off
	v_lshl_add_u64 v[182:183], v[188:189], 0, s[64:65]
	s_mov_b32 m0, s94
	s_nop 0
	global_load_lds_dwordx4 v[182:183], off
	v_lshl_add_u64 v[182:183], v[190:191], 0, s[64:65]
	s_mov_b32 m0, s95
	s_nop 0
	global_load_lds_dwordx4 v[182:183], off
	s_waitcnt vmcnt(8)
	s_waitcnt lgkmcnt(0)
	s_barrier
	s_setprio 1
	s_waitcnt lgkmcnt(0)
	v_mfma_f32_16x16x32_bf16 v[66:69], v[138:141], v[174:177], v[66:69]
	v_mfma_f32_16x16x32_bf16 v[66:69], v[142:145], v[178:181], v[66:69]
	v_mfma_f32_16x16x32_bf16 v[62:65], v[150:153], v[174:177], v[62:65]
	v_mfma_f32_16x16x32_bf16 v[62:65], v[154:157], v[178:181], v[62:65]
	v_mfma_f32_16x16x32_bf16 v[50:53], v[138:141], v[196:199], v[50:53]
	v_mfma_f32_16x16x32_bf16 v[50:53], v[142:145], v[200:203], v[50:53]
	v_mfma_f32_16x16x32_bf16 v[46:49], v[150:153], v[196:199], v[46:49]
	v_mfma_f32_16x16x32_bf16 v[46:49], v[154:157], v[200:203], v[46:49]
	v_mfma_f32_16x16x32_bf16 v[34:37], v[138:141], v[204:207], v[34:37]
	v_mfma_f32_16x16x32_bf16 v[34:37], v[142:145], v[208:211], v[34:37]
	v_mfma_f32_16x16x32_bf16 v[26:29], v[150:153], v[204:207], v[26:29]
	v_mfma_f32_16x16x32_bf16 v[26:29], v[154:157], v[208:211], v[26:29]
	v_mfma_f32_16x16x32_bf16 v[14:17], v[138:141], v[212:215], v[14:17]
	v_mfma_f32_16x16x32_bf16 v[14:17], v[142:145], v[216:219], v[14:17]
	v_mfma_f32_16x16x32_bf16 v[10:13], v[150:153], v[212:215], v[10:13]
	v_mfma_f32_16x16x32_bf16 v[10:13], v[154:157], v[216:219], v[10:13]
	s_setprio 0
	s_setprio 1
	v_mfma_f32_16x16x32_bf16 v[58:61], v[158:161], v[174:177], v[58:61]
	v_mfma_f32_16x16x32_bf16 v[58:61], v[162:165], v[178:181], v[58:61]
	v_mfma_f32_16x16x32_bf16 v[54:57], v[166:169], v[174:177], v[54:57]
	v_mfma_f32_16x16x32_bf16 v[54:57], v[170:173], v[178:181], v[54:57]
	v_mfma_f32_16x16x32_bf16 v[42:45], v[158:161], v[196:199], v[42:45]
	v_mfma_f32_16x16x32_bf16 v[42:45], v[162:165], v[200:203], v[42:45]
	v_mfma_f32_16x16x32_bf16 v[38:41], v[166:169], v[196:199], v[38:41]
	v_mfma_f32_16x16x32_bf16 v[38:41], v[170:173], v[200:203], v[38:41]
	v_mfma_f32_16x16x32_bf16 v[22:25], v[158:161], v[204:207], v[22:25]
	v_mfma_f32_16x16x32_bf16 v[22:25], v[162:165], v[208:211], v[22:25]
	v_mfma_f32_16x16x32_bf16 v[18:21], v[166:169], v[204:207], v[18:21]
	v_mfma_f32_16x16x32_bf16 v[18:21], v[170:173], v[208:211], v[18:21]
	v_mfma_f32_16x16x32_bf16 v[6:9], v[158:161], v[212:215], v[6:9]
	v_mfma_f32_16x16x32_bf16 v[6:9], v[162:165], v[216:219], v[6:9]
	v_mfma_f32_16x16x32_bf16 v[2:5], v[166:169], v[212:215], v[2:5]
	v_mfma_f32_16x16x32_bf16 v[2:5], v[170:173], v[216:219], v[2:5]
	s_setprio 0
	s_barrier
	s_movk_i32 s28, 0x100
	s_andn2_b64 vcc, exec, s[4:5]
	s_mov_b64 s[26:27], -1
	s_mov_b64 s[4:5], 0
	s_cbranch_vccz .LBB0_766
	s_and_b64 vcc, exec, s[10:11]
	s_cbranch_vccz .LBB0_769
	s_barrier

; #define PG8_STAGE(bufoff, gbase, voff) do { _Pragma("unroll") for (int _i = 0; _i < 2; ++_i) \
;         __builtin_amdgcn_global_load_lds((const unsigned*)((const char*)(gbase) + (voff)[_i]), (PG8_LAS unsigned*)(lds + (bufoff) + ldsw + _i * 8192), 16, 0, 0); } while (0)
; #define PG8_LDA(dst, b, h) do { _Pragma("unroll") for (int m = 0; m < 4; ++m) _Pragma("unroll") for (int k = 0; k < 2; ++k) dst[m][k] = *(const PG8_LAS bf16x8*)(lds + PG8_SA(b, h) + aoff + m * 2048 + k * 1024); } while (0)
; #define PG8_LDB(dst, b, h) do { _Pragma("unroll") for (int n = 0; n < 2; ++n) _Pragma("unroll") for (int k = 0; k < 2; ++k) dst[n][k] = *(const PG8_LAS bf16x8*)(lds + PG8_SB(b, h) + boff + n * 2048 + k * 1024); } while (0)
; #define PG8_MMA(ai, bj, At, Bt) do { __builtin_amdgcn_s_setprio(1); _Pragma("unroll") for (int m = 0; m < 4; ++m) _Pragma("unroll") for (int n = 0; n < 2; ++n) _Pragma("unroll") for (int k = 0; k < 2; ++k) \
;         acc[ai][bj][m][n] = __builtin_amdgcn_mfma_f32_16x16x32_bf16(Bt[n][k], At[m][k], acc[ai][bj][m][n], 0, 0, 0); __builtin_amdgcn_s_setprio(0); } while (0)
; #define PG8_WAIT_V(n) asm volatile("s_waitcnt vmcnt(" #n ")" ::: "memory")
; #define PG8_WAIT_L(n) asm volatile("s_waitcnt lgkmcnt(" #n ")" ::: "memory")
; #define PG8_BAR __builtin_amdgcn_s_barrier()
; #define PG8_SCHED __builtin_amdgcn_sched_barrier(0)
;     ...
;             const bool last = (t == nt - 2);
;             const char* a1 = cA + (size_t)(t + 1) * kstep;
;             const char* a2 = last ? nA : cA + (size_t)(t + 2) * kstep; const char* b2 = last ? nB : cB + (size_t)(t + 2) * kstep;
;             const char* a3 = a2 + kstep; const char* b3 = b2 + kstep;
;             if (last && has_next) S.a_ready(nxt);
;             if constexpr (SP2) {
;             PG8_LDB(B0, 0, 0); PG8_LDB(B1, 0, 1); PG8_SCHED; PG8_LDA(At, 0, 0); PG8_STAGE(PG8_SA(1, 1), a1 + hstepA, voffA);
;             PG8_WAIT_V(8); PG8_WAIT_L(0); PG8_BAR; PG8_MMA(0, 0, At, B0); PG8_MMA(0, 1, At, B1); PG8_BAR; PG8_SCHED;
;             PG8_LDA(At, 0, 1); PG8_STAGE(PG8_SB(0, 0), b2, voffB); PG8_STAGE(PG8_SB(0, 1), b2 + hstep, voffB); PG8_STAGE(PG8_SA(0, 0), a2, voffA);
;             PG8_WAIT_V(8); PG8_WAIT_L(0); PG8_BAR; PG8_MMA(1, 0, At, B0); PG8_MMA(1, 1, At, B1); PG8_BAR; PG8_SCHED;
.LBB0_1064:
	s_add_u32 s30, s28, 0x100
	s_addc_u32 s31, s29, 0
	s_add_i32 s23, 0, 0x10000
	s_cmp_eq_u32 s40, s19
	s_cselect_b32 s93, s91, s31
	s_cselect_b32 s92, s90, s30
	v_add_u32_e32 v32, s23, v239
	s_cselect_b32 s39, s95, s17
	s_cselect_b32 s38, s94, s9
	s_add_i32 s25, 0, 0x14000
	ds_read_b128 v[72:75], v32
	ds_read_b128 v[76:79], v32 offset:1024
	ds_read_b128 v[80:83], v32 offset:2048
	ds_read_b128 v[88:91], v32 offset:3072
	v_add_u32_e32 v32, s25, v239
	ds_read_b128 v[152:155], v32
	ds_read_b128 v[156:159], v32 offset:1024
	ds_read_b128 v[160:163], v32 offset:2048
	ds_read_b128 v[164:167], v32 offset:3072
	v_lshl_add_u64 v[34:35], s[28:29], 0, v[196:197]
	s_add_i32 m0, s56, 0xc000
	ds_read_b128 v[168:171], v251
	ds_read_b128 v[172:175], v251 offset:1024
	ds_read_b128 v[176:179], v251 offset:2048
	ds_read_b128 v[200:203], v251 offset:3072
	ds_read_b128 v[204:207], v251 offset:4096
	ds_read_b128 v[208:211], v251 offset:5120
	ds_read_b128 v[212:215], v251 offset:6144
	ds_read_b128 v[216:219], v251 offset:7168
	global_load_lds_dwordx4 v[34:35], off
	v_lshl_add_u64 v[34:35], s[28:29], 0, v[198:199]
	s_add_i32 m0, s56, 0xe000
	s_nop 0
	global_load_lds_dwordx4 v[34:35], off
	s_waitcnt vmcnt(8)
	s_waitcnt lgkmcnt(0)
	s_barrier
	s_setprio 1
	s_waitcnt lgkmcnt(0)
	v_mfma_f32_16x16x32_bf16 v[84:87], v[72:75], v[168:171], v[84:87]
	v_mfma_f32_16x16x32_bf16 v[84:87], v[76:79], v[172:175], v[84:87]
	v_mfma_f32_16x16x32_bf16 v[148:151], v[80:83], v[168:171], v[148:151]
	v_mfma_f32_16x16x32_bf16 v[148:151], v[88:91], v[172:175], v[148:151]
	v_mfma_f32_16x16x32_bf16 v[136:139], v[72:75], v[176:179], v[136:139]
	v_mfma_f32_16x16x32_bf16 v[136:139], v[76:79], v[200:203], v[136:139]
	v_mfma_f32_16x16x32_bf16 v[132:135], v[80:83], v[176:179], v[132:135]
	v_mfma_f32_16x16x32_bf16 v[132:135], v[88:91], v[200:203], v[132:135]
	v_mfma_f32_16x16x32_bf16 v[120:123], v[72:75], v[204:207], v[120:123]
	v_mfma_f32_16x16x32_bf16 v[120:123], v[76:79], v[208:211], v[120:123]
	v_mfma_f32_16x16x32_bf16 v[116:119], v[80:83], v[204:207], v[116:119]
	v_mfma_f32_16x16x32_bf16 v[116:119], v[88:91], v[208:211], v[116:119]
	v_mfma_f32_16x16x32_bf16 v[104:107], v[72:75], v[212:215], v[104:107]
	v_mfma_f32_16x16x32_bf16 v[104:107], v[76:79], v[216:219], v[104:107]
	v_mfma_f32_16x16x32_bf16 v[100:103], v[80:83], v[212:215], v[100:103]
	v_mfma_f32_16x16x32_bf16 v[100:103], v[88:91], v[216:219], v[100:103]
	s_setprio 0
	s_setprio 1
	v_mfma_f32_16x16x32_bf16 v[144:147], v[152:155], v[168:171], v[144:147]
	v_mfma_f32_16x16x32_bf16 v[144:147], v[156:159], v[172:175], v[144:147]
	v_mfma_f32_16x16x32_bf16 v[140:143], v[160:163], v[168:171], v[140:143]
	v_mfma_f32_16x16x32_bf16 v[140:143], v[164:167], v[172:175], v[140:143]
	v_mfma_f32_16x16x32_bf16 v[128:131], v[152:155], v[176:179], v[128:131]
	v_mfma_f32_16x16x32_bf16 v[128:131], v[156:159], v[200:203], v[128:131]
	v_mfma_f32_16x16x32_bf16 v[124:127], v[160:163], v[176:179], v[124:127]
	v_mfma_f32_16x16x32_bf16 v[124:127], v[164:167], v[200:203], v[124:127]
	v_mfma_f32_16x16x32_bf16 v[112:115], v[152:155], v[204:207], v[112:115]
	v_mfma_f32_16x16x32_bf16 v[112:115], v[156:159], v[208:211], v[112:115]
	v_mfma_f32_16x16x32_bf16 v[108:111], v[160:163], v[204:207], v[108:111]
	v_mfma_f32_16x16x32_bf16 v[108:111], v[164:167], v[208:211], v[108:111]
	v_mfma_f32_16x16x32_bf16 v[96:99], v[152:155], v[212:215], v[96:99]
	v_mfma_f32_16x16x32_bf16 v[96:99], v[156:159], v[216:219], v[96:99]
	v_mfma_f32_16x16x32_bf16 v[92:95], v[160:163], v[212:215], v[92:95]
	v_mfma_f32_16x16x32_bf16 v[92:95], v[164:167], v[216:219], v[92:95]
	s_setprio 0
	s_barrier
	s_add_i32 s23, s23, s3
	v_lshl_add_u64 v[186:187], s[38:39], 0, v[30:31]
	s_mov_b32 m0, s23
	ds_read_b128 v[168:171], v251 offset:16384
	ds_read_b128 v[172:175], v251 offset:17408
	ds_read_b128 v[176:179], v251 offset:18432
	ds_read_b128 v[200:203], v251 offset:19456
	ds_read_b128 v[204:207], v251 offset:20480
	ds_read_b128 v[208:211], v251 offset:21504
	ds_read_b128 v[212:215], v251 offset:22528
	ds_read_b128 v[216:219], v251 offset:23552
	global_load_lds_dwordx4 v[186:187], off
	s_add_i32 m0, s23, 0x2000
	s_add_u32 s28, s38, 0x80000
	v_lshl_add_u64 v[188:189], s[38:39], 0, v[180:181]
	s_addc_u32 s29, s39, 0
	s_add_i32 s23, s25, s3
	global_load_lds_dwordx4 v[188:189], off
	v_lshl_add_u64 v[34:35], s[28:29], 0, v[30:31]
	s_mov_b32 m0, s23
	v_lshl_add_u64 v[190:191], s[92:93], 0, v[30:31]
	global_load_lds_dwordx4 v[34:35], off
	v_lshl_add_u64 v[34:35], s[28:29], 0, v[180:181]
	s_add_i32 m0, s23, 0x2000
	v_lshl_add_u64 v[220:221], s[92:93], 0, v[180:181]
	global_load_lds_dwordx4 v[34:35], off
	s_mov_b32 m0, s56
	s_nop 0
	global_load_lds_dwordx4 v[190:191], off
	s_mov_b32 m0, s41
	s_nop 0
	global_load_lds_dwordx4 v[220:221], off
	s_waitcnt vmcnt(8)
	s_waitcnt lgkmcnt(0)
	s_barrier
; #define PG8_STAGE(bufoff, gbase, voff) do { _Pragma("unroll") for (int _i = 0; _i < 2; ++_i) \
;         __builtin_amdgcn_global_load_lds((const unsigned*)((const char*)(gbase) + (voff)[_i]), (PG8_LAS unsigned*)(lds + (bufoff) + ldsw + _i * 8192), 16, 0, 0); } while (0)
; #define PG8_LDA(dst, b, h) do { _Pragma("unroll") for (int m = 0; m < 4; ++m) _Pragma("unroll") for (int k = 0; k < 2; ++k) dst[m][k] = *(const PG8_LAS bf16x8*)(lds + PG8_SA(b, h) + aoff + m * 2048 + k * 1024); } while (0)
; #define PG8_LDB(dst, b, h) do { _Pragma("unroll") for (int n = 0; n < 2; ++n) _Pragma("unroll") for (int k = 0; k < 2; ++k) dst[n][k] = *(const PG8_LAS bf16x8*)(lds + PG8_SB(b, h) + boff + n * 2048 + k * 1024); } while (0)
; #define PG8_MMA(ai, bj, At, Bt) do { __builtin_amdgcn_s_setprio(1); _Pragma("unroll") for (int m = 0; m < 4; ++m) _Pragma("unroll") for (int n = 0; n < 2; ++n) _Pragma("unroll") for (int k = 0; k < 2; ++k) \
;         acc[ai][bj][m][n] = __builtin_amdgcn_mfma_f32_16x16x32_bf16(Bt[n][k], At[m][k], acc[ai][bj][m][n], 0, 0, 0); __builtin_amdgcn_s_setprio(0); } while (0)
; #define PG8_WAIT_V(n) asm volatile("s_waitcnt vmcnt(" #n ")" ::: "memory")
; #define PG8_WAIT_L(n) asm volatile("s_waitcnt lgkmcnt(" #n ")" ::: "memory")
; #define PG8_BAR __builtin_amdgcn_s_barrier()
; #define PG8_SCHED __builtin_amdgcn_sched_barrier(0)
;     ...
;             PG8_WAIT_V(8); PG8_WAIT_L(0); PG8_BAR; PG8_MMA(1, 0, At, B0); PG8_MMA(1, 1, At, B1); PG8_BAR; PG8_SCHED;
;             PG8_LDB(B0, 1, 0); PG8_LDB(B1, 1, 1); PG8_SCHED; PG8_LDA(At, 1, 0); PG8_STAGE(PG8_SA(0, 1), a2 + hstepA, voffA);
;             PG8_WAIT_V(8); PG8_WAIT_L(0); PG8_BAR; PG8_MMA(0, 0, At, B0); PG8_MMA(0, 1, At, B1); PG8_BAR; PG8_SCHED;
	s_setprio 1
	s_waitcnt lgkmcnt(0)
	v_mfma_f32_16x16x32_bf16 v[68:71], v[72:75], v[168:171], v[68:71]
	v_mfma_f32_16x16x32_bf16 v[68:71], v[76:79], v[172:175], v[68:71]
	v_mfma_f32_16x16x32_bf16 v[64:67], v[80:83], v[168:171], v[64:67]
	v_mfma_f32_16x16x32_bf16 v[64:67], v[88:91], v[172:175], v[64:67]
	v_mfma_f32_16x16x32_bf16 v[52:55], v[72:75], v[176:179], v[52:55]
	v_mfma_f32_16x16x32_bf16 v[52:55], v[76:79], v[200:203], v[52:55]
	v_mfma_f32_16x16x32_bf16 v[48:51], v[80:83], v[176:179], v[48:51]
	v_mfma_f32_16x16x32_bf16 v[48:51], v[88:91], v[200:203], v[48:51]
	v_mfma_f32_16x16x32_bf16 v[34:37], v[72:75], v[204:207], v[36:39]
	v_mfma_f32_16x16x32_bf16 v[34:37], v[76:79], v[208:211], v[34:37]
	v_mfma_f32_16x16x32_bf16 v[26:29], v[80:83], v[204:207], v[26:29]
	v_mfma_f32_16x16x32_bf16 v[26:29], v[88:91], v[208:211], v[26:29]
	v_mfma_f32_16x16x32_bf16 v[14:17], v[72:75], v[212:215], v[14:17]
	v_mfma_f32_16x16x32_bf16 v[14:17], v[76:79], v[216:219], v[14:17]
	v_mfma_f32_16x16x32_bf16 v[10:13], v[80:83], v[212:215], v[10:13]
	v_mfma_f32_16x16x32_bf16 v[10:13], v[88:91], v[216:219], v[10:13]
	s_setprio 0
	s_setprio 1
	v_mfma_f32_16x16x32_bf16 v[60:63], v[152:155], v[168:171], v[60:63]
	v_mfma_f32_16x16x32_bf16 v[60:63], v[156:159], v[172:175], v[60:63]
	v_mfma_f32_16x16x32_bf16 v[56:59], v[160:163], v[168:171], v[56:59]
	v_mfma_f32_16x16x32_bf16 v[56:59], v[164:167], v[172:175], v[56:59]
	v_mfma_f32_16x16x32_bf16 v[44:47], v[152:155], v[176:179], v[44:47]
	v_mfma_f32_16x16x32_bf16 v[44:47], v[156:159], v[200:203], v[44:47]
	v_mfma_f32_16x16x32_bf16 v[38:41], v[160:163], v[176:179], v[40:43]
	v_mfma_f32_16x16x32_bf16 v[40:43], v[164:167], v[200:203], v[38:41]
	v_mfma_f32_16x16x32_bf16 v[22:25], v[152:155], v[204:207], v[22:25]
	v_mfma_f32_16x16x32_bf16 v[22:25], v[156:159], v[208:211], v[22:25]
	v_mfma_f32_16x16x32_bf16 v[18:21], v[160:163], v[204:207], v[18:21]
	v_mfma_f32_16x16x32_bf16 v[18:21], v[164:167], v[208:211], v[18:21]
	v_mfma_f32_16x16x32_bf16 v[6:9], v[152:155], v[212:215], v[6:9]
	v_mfma_f32_16x16x32_bf16 v[6:9], v[156:159], v[216:219], v[6:9]
	v_mfma_f32_16x16x32_bf16 v[2:5], v[160:163], v[212:215], v[2:5]
	v_mfma_f32_16x16x32_bf16 v[2:5], v[164:167], v[216:219], v[2:5]
	s_setprio 0
	s_barrier
	s_add_i32 s23, 0, 0x18000
	v_add_u32_e32 v32, s23, v239
	s_add_i32 s25, 0, 0x1c000
	ds_read_b128 v[72:75], v32
	ds_read_b128 v[76:79], v32 offset:1024
	ds_read_b128 v[80:83], v32 offset:2048
	ds_read_b128 v[88:91], v32 offset:3072
	v_add_u32_e32 v32, s25, v239
	ds_read_b128 v[152:155], v32
	ds_read_b128 v[156:159], v32 offset:1024
	ds_read_b128 v[160:163], v32 offset:2048
	ds_read_b128 v[164:167], v32 offset:3072
	s_add_u32 s28, s92, 0x80000
	s_addc_u32 s29, s93, 0
	s_mov_b32 m0, s74
	v_lshl_add_u64 v[38:39], s[28:29], 0, v[30:31]
	ds_read_b128 v[168:171], v251 offset:32768
	ds_read_b128 v[172:175], v251 offset:33792
	ds_read_b128 v[176:179], v251 offset:34816
	ds_read_b128 v[200:203], v251 offset:35840
	ds_read_b128 v[204:207], v251 offset:36864
	ds_read_b128 v[208:211], v251 offset:37888
	ds_read_b128 v[212:215], v251 offset:38912
	ds_read_b128 v[216:219], v251 offset:39936
	global_load_lds_dwordx4 v[38:39], off
	v_lshl_add_u64 v[38:39], s[28:29], 0, v[180:181]
	s_mov_b32 m0, s96
	s_nop 0
	global_load_lds_dwordx4 v[38:39], off
	s_waitcnt vmcnt(8)
	s_waitcnt lgkmcnt(0)
	s_barrier
	s_setprio 1
	s_waitcnt lgkmcnt(0)
	v_mfma_f32_16x16x32_bf16 v[84:87], v[72:75], v[168:171], v[84:87]
	v_mfma_f32_16x16x32_bf16 v[84:87], v[76:79], v[172:175], v[84:87]
	v_mfma_f32_16x16x32_bf16 v[148:151], v[80:83], v[168:171], v[148:151]
	v_mfma_f32_16x16x32_bf16 v[148:151], v[88:91], v[172:175], v[148:151]
	v_mfma_f32_16x16x32_bf16 v[136:139], v[72:75], v[176:179], v[136:139]
	v_mfma_f32_16x16x32_bf16 v[136:139], v[76:79], v[200:203], v[136:139]
	v_mfma_f32_16x16x32_bf16 v[132:135], v[80:83], v[176:179], v[132:135]
	v_mfma_f32_16x16x32_bf16 v[132:135], v[88:91], v[200:203], v[132:135]
	v_mfma_f32_16x16x32_bf16 v[120:123], v[72:75], v[204:207], v[120:123]
	v_mfma_f32_16x16x32_bf16 v[120:123], v[76:79], v[208:211], v[120:123]
	v_mfma_f32_16x16x32_bf16 v[116:119], v[80:83], v[204:207], v[116:119]
	v_mfma_f32_16x16x32_bf16 v[116:119], v[88:91], v[208:211], v[116:119]
	v_mfma_f32_16x16x32_bf16 v[104:107], v[72:75], v[212:215], v[104:107]
	v_mfma_f32_16x16x32_bf16 v[104:107], v[76:79], v[216:219], v[104:107]
	v_mfma_f32_16x16x32_bf16 v[100:103], v[80:83], v[212:215], v[100:103]
	v_mfma_f32_16x16x32_bf16 v[100:103], v[88:91], v[216:219], v[100:103]
	s_setprio 0
	s_setprio 1
	v_mfma_f32_16x16x32_bf16 v[144:147], v[152:155], v[168:171], v[144:147]
	v_mfma_f32_16x16x32_bf16 v[144:147], v[156:159], v[172:175], v[144:147]
	v_mfma_f32_16x16x32_bf16 v[140:143], v[160:163], v[168:171], v[140:143]
	v_mfma_f32_16x16x32_bf16 v[140:143], v[164:167], v[172:175], v[140:143]
	v_mfma_f32_16x16x32_bf16 v[128:131], v[152:155], v[176:179], v[128:131]
	v_mfma_f32_16x16x32_bf16 v[128:131], v[156:159], v[200:203], v[128:131]
	v_mfma_f32_16x16x32_bf16 v[124:127], v[160:163], v[176:179], v[124:127]
	v_mfma_f32_16x16x32_bf16 v[124:127], v[164:167], v[200:203], v[124:127]
	v_mfma_f32_16x16x32_bf16 v[112:115], v[152:155], v[204:207], v[112:115]
	v_mfma_f32_16x16x32_bf16 v[112:115], v[156:159], v[208:211], v[112:115]
	v_mfma_f32_16x16x32_bf16 v[108:111], v[160:163], v[204:207], v[108:111]
	v_mfma_f32_16x16x32_bf16 v[108:111], v[164:167], v[208:211], v[108:111]
	v_mfma_f32_16x16x32_bf16 v[96:99], v[152:155], v[212:215], v[96:99]
	v_mfma_f32_16x16x32_bf16 v[96:99], v[156:159], v[216:219], v[96:99]
	v_mfma_f32_16x16x32_bf16 v[92:95], v[160:163], v[212:215], v[92:95]
	v_mfma_f32_16x16x32_bf16 v[92:95], v[164:167], v[216:219], v[92:95]
	s_setprio 0
	s_barrier
; #define PG8_STAGE(bufoff, gbase, voff) do { _Pragma("unroll") for (int _i = 0; _i < 2; ++_i) \
;         __builtin_amdgcn_global_load_lds((const unsigned*)((const char*)(gbase) + (voff)[_i]), (PG8_LAS unsigned*)(lds + (bufoff) + ldsw + _i * 8192), 16, 0, 0); } while (0)
; #define PG8_LDA(dst, b, h) do { _Pragma("unroll") for (int m = 0; m < 4; ++m) _Pragma("unroll") for (int k = 0; k < 2; ++k) dst[m][k] = *(const PG8_LAS bf16x8*)(lds + PG8_SA(b, h) + aoff + m * 2048 + k * 1024); } while (0)
; #define PG8_MMA(ai, bj, At, Bt) do { __builtin_amdgcn_s_setprio(1); _Pragma("unroll") for (int m = 0; m < 4; ++m) _Pragma("unroll") for (int n = 0; n < 2; ++n) _Pragma("unroll") for (int k = 0; k < 2; ++k) \
;         acc[ai][bj][m][n] = __builtin_amdgcn_mfma_f32_16x16x32_bf16(Bt[n][k], At[m][k], acc[ai][bj][m][n], 0, 0, 0); __builtin_amdgcn_s_setprio(0); } while (0)
; #define PG8_WAIT_V(n) asm volatile("s_waitcnt vmcnt(" #n ")" ::: "memory")
; #define PG8_WAIT_L(n) asm volatile("s_waitcnt lgkmcnt(" #n ")" ::: "memory")
; #define PG8_BAR __builtin_amdgcn_s_barrier()
; #define PG8_SCHED __builtin_amdgcn_sched_barrier(0)
;     ...
;         for (int t = 0; t < nt; t += 2) {
;             const bool last = (t == nt - 2);
;             const char* a1 = cA + (size_t)(t + 1) * kstep;
;             const char* a2 = last ? nA : cA + (size_t)(t + 2) * kstep; const char* b2 = last ? nB : cB + (size_t)(t + 2) * kstep;
;     ...
;             PG8_LDA(At, 1, 1); PG8_STAGE(PG8_SB(1, 0), b3, voffB); PG8_STAGE(PG8_SB(1, 1), b3 + hstep, voffB); PG8_STAGE(PG8_SA(1, 0), a3, voffA);
;             PG8_WAIT_V(8); PG8_WAIT_L(0); PG8_BAR; PG8_MMA(1, 0, At, B0); PG8_MMA(1, 1, At, B1); PG8_BAR; PG8_SCHED;
	s_add_i32 s23, s23, s3
	v_lshl_add_u64 v[38:39], v[186:187], 0, s[64:65]
	s_mov_b32 m0, s23
	ds_read_b128 v[168:171], v251 offset:49152
	ds_read_b128 v[172:175], v251 offset:50176
	ds_read_b128 v[176:179], v251 offset:51200
	ds_read_b128 v[200:203], v251 offset:52224
	ds_read_b128 v[204:207], v251 offset:53248
	ds_read_b128 v[208:211], v251 offset:54272
	ds_read_b128 v[212:215], v251 offset:55296
	ds_read_b128 v[216:219], v251 offset:56320
	global_load_lds_dwordx4 v[38:39], off
	s_add_i32 m0, s23, 0x2000
	s_add_u32 s28, s38, 0x80080
	v_lshl_add_u64 v[38:39], v[188:189], 0, s[64:65]
	s_addc_u32 s29, s39, 0
	s_add_i32 s23, s25, s3
	global_load_lds_dwordx4 v[38:39], off
	v_lshl_add_u64 v[38:39], s[28:29], 0, v[30:31]
	s_mov_b32 m0, s23
	s_nop 0
	global_load_lds_dwordx4 v[38:39], off
	v_lshl_add_u64 v[38:39], s[28:29], 0, v[180:181]
	s_add_i32 m0, s23, 0x2000
	s_nop 0
	global_load_lds_dwordx4 v[38:39], off
	v_lshl_add_u64 v[38:39], v[190:191], 0, s[64:65]
	s_mov_b32 m0, s53
	s_nop 0
	global_load_lds_dwordx4 v[38:39], off
	v_lshl_add_u64 v[38:39], v[220:221], 0, s[64:65]
	s_mov_b32 m0, s4
	s_nop 0
	global_load_lds_dwordx4 v[38:39], off
	s_waitcnt vmcnt(8)
	s_waitcnt lgkmcnt(0)
	s_barrier
	s_setprio 1
	s_waitcnt lgkmcnt(0)
	v_mfma_f32_16x16x32_bf16 v[68:71], v[72:75], v[168:171], v[68:71]
	v_mfma_f32_16x16x32_bf16 v[68:71], v[76:79], v[172:175], v[68:71]
	v_mfma_f32_16x16x32_bf16 v[64:67], v[80:83], v[168:171], v[64:67]
	v_mfma_f32_16x16x32_bf16 v[64:67], v[88:91], v[172:175], v[64:67]
	v_mfma_f32_16x16x32_bf16 v[52:55], v[72:75], v[176:179], v[52:55]
	v_mfma_f32_16x16x32_bf16 v[52:55], v[76:79], v[200:203], v[52:55]
	v_mfma_f32_16x16x32_bf16 v[48:51], v[80:83], v[176:179], v[48:51]
	v_mfma_f32_16x16x32_bf16 v[48:51], v[88:91], v[200:203], v[48:51]
	v_mfma_f32_16x16x32_bf16 v[34:37], v[72:75], v[204:207], v[34:37]
	v_mfma_f32_16x16x32_bf16 v[36:39], v[76:79], v[208:211], v[34:37]
	v_mfma_f32_16x16x32_bf16 v[26:29], v[80:83], v[204:207], v[26:29]
	v_mfma_f32_16x16x32_bf16 v[26:29], v[88:91], v[208:211], v[26:29]
	v_mfma_f32_16x16x32_bf16 v[14:17], v[72:75], v[212:215], v[14:17]
	v_mfma_f32_16x16x32_bf16 v[14:17], v[76:79], v[216:219], v[14:17]
	v_mfma_f32_16x16x32_bf16 v[10:13], v[80:83], v[212:215], v[10:13]
	v_mfma_f32_16x16x32_bf16 v[10:13], v[88:91], v[216:219], v[10:13]
	s_setprio 0
	s_setprio 1
	v_mfma_f32_16x16x32_bf16 v[60:63], v[152:155], v[168:171], v[60:63]
	v_mfma_f32_16x16x32_bf16 v[60:63], v[156:159], v[172:175], v[60:63]
	v_mfma_f32_16x16x32_bf16 v[56:59], v[160:163], v[168:171], v[56:59]
	v_mfma_f32_16x16x32_bf16 v[56:59], v[164:167], v[172:175], v[56:59]
	v_mfma_f32_16x16x32_bf16 v[44:47], v[152:155], v[176:179], v[44:47]
	v_mfma_f32_16x16x32_bf16 v[44:47], v[156:159], v[200:203], v[44:47]
	v_mfma_f32_16x16x32_bf16 v[40:43], v[160:163], v[176:179], v[40:43]
	v_mfma_f32_16x16x32_bf16 v[40:43], v[164:167], v[200:203], v[40:43]
	v_mfma_f32_16x16x32_bf16 v[22:25], v[152:155], v[204:207], v[22:25]
	v_mfma_f32_16x16x32_bf16 v[22:25], v[156:159], v[208:211], v[22:25]
	v_mfma_f32_16x16x32_bf16 v[18:21], v[160:163], v[204:207], v[18:21]
	v_mfma_f32_16x16x32_bf16 v[18:21], v[164:167], v[208:211], v[18:21]
	v_mfma_f32_16x16x32_bf16 v[6:9], v[152:155], v[212:215], v[6:9]
	v_mfma_f32_16x16x32_bf16 v[6:9], v[156:159], v[216:219], v[6:9]
	v_mfma_f32_16x16x32_bf16 v[2:5], v[160:163], v[212:215], v[2:5]
	v_mfma_f32_16x16x32_bf16 v[2:5], v[164:167], v[216:219], v[2:5]
	s_setprio 0
	s_barrier
	s_add_i32 s23, s19, 2
	s_add_u32 s9, s9, 0x100
	s_addc_u32 s17, s17, 0
	s_cmp_ge_i32 s19, s40
	s_mov_b64 s[28:29], s[30:31]
	s_mov_b32 s19, s23
	s_cbranch_scc0 .LBB0_1064
	s_and_b64 vcc, exec, s[14:15]
	s_cbranch_vccz .LBB0_1067
	s_barrier

; #define PG8_STAGE(bufoff, gbase, voff) do { _Pragma("unroll") for (int _i = 0; _i < 2; ++_i) \
;         __builtin_amdgcn_global_load_lds((const unsigned*)((const char*)(gbase) + (voff)[_i]), (PG8_LAS unsigned*)(lds + (bufoff) + ldsw + _i * 8192), 16, 0, 0); } while (0)
; #define PG8_LDA(dst, b, h) do { _Pragma("unroll") for (int m = 0; m < 4; ++m) _Pragma("unroll") for (int k = 0; k < 2; ++k) dst[m][k] = *(const PG8_LAS bf16x8*)(lds + PG8_SA(b, h) + aoff + m * 2048 + k * 1024); } while (0)
; #define PG8_LDB(dst, b, h) do { _Pragma("unroll") for (int n = 0; n < 2; ++n) _Pragma("unroll") for (int k = 0; k < 2; ++k) dst[n][k] = *(const PG8_LAS bf16x8*)(lds + PG8_SB(b, h) + boff + n * 2048 + k * 1024); } while (0)
; #define PG8_MMA(ai, bj, At, Bt) do { __builtin_amdgcn_s_setprio(1); _Pragma("unroll") for (int m = 0; m < 4; ++m) _Pragma("unroll") for (int n = 0; n < 2; ++n) _Pragma("unroll") for (int k = 0; k < 2; ++k) \
;         acc[ai][bj][m][n] = __builtin_amdgcn_mfma_f32_16x16x32_bf16(Bt[n][k], At[m][k], acc[ai][bj][m][n], 0, 0, 0); __builtin_amdgcn_s_setprio(0); } while (0)
; #define PG8_WAIT_V(n) asm volatile("s_waitcnt vmcnt(" #n ")" ::: "memory")
; #define PG8_WAIT_L(n) asm volatile("s_waitcnt lgkmcnt(" #n ")" ::: "memory")
; #define PG8_BAR __builtin_amdgcn_s_barrier()
; #define PG8_SCHED __builtin_amdgcn_sched_barrier(0)
;     ...
;             const bool last = (t == nt - 2);
;             const char* a1 = cA + (size_t)(t + 1) * kstep;
;             const char* a2 = last ? nA : cA + (size_t)(t + 2) * kstep; const char* b2 = last ? nB : cB + (size_t)(t + 2) * kstep;
;             const char* a3 = a2 + kstep; const char* b3 = b2 + kstep;
;             if (last && has_next) S.a_ready(nxt);
;             if constexpr (SP2) {
;             PG8_LDB(B0, 0, 0); PG8_LDB(B1, 0, 1); PG8_SCHED; PG8_LDA(At, 0, 0); PG8_STAGE(PG8_SA(1, 1), a1 + hstepA, voffA);
;             PG8_WAIT_V(8); PG8_WAIT_L(0); PG8_BAR; PG8_MMA(0, 0, At, B0); PG8_MMA(0, 1, At, B1); PG8_BAR; PG8_SCHED;
;             PG8_LDA(At, 0, 1); PG8_STAGE(PG8_SB(0, 0), b2, voffB); PG8_STAGE(PG8_SB(0, 1), b2 + hstep, voffB); PG8_STAGE(PG8_SA(0, 0), a2, voffA);
;             PG8_WAIT_V(8); PG8_WAIT_L(0); PG8_BAR; PG8_MMA(1, 0, At, B0); PG8_MMA(1, 1, At, B1); PG8_BAR; PG8_SCHED;
.LBB0_1332:
	s_add_u32 s26, s24, 0xfff80080
	s_addc_u32 s27, s25, -1
	s_add_i32 s42, 0, 0x10000
	s_cmp_eq_u32 s79, 28
	s_cselect_b32 s29, s11, s27
	s_cselect_b32 s28, s48, s26
	s_cselect_b32 s27, s9, s78
	s_cselect_b32 s26, s33, s74
	s_add_i32 s46, 0, 0x14000
	v_add_u32_e32 v106, s42, v31
	v_add_u32_e32 v174, s46, v31
	ds_read_b128 v[94:97], v106
	ds_read_b128 v[98:101], v106 offset:1024
	ds_read_b128 v[102:105], v106 offset:2048
	ds_read_b128 v[106:109], v106 offset:3072
	ds_read_b128 v[160:163], v174
	ds_read_b128 v[164:167], v174 offset:1024
	ds_read_b128 v[170:173], v174 offset:2048
	ds_read_b128 v[174:177], v174 offset:3072
	v_lshl_add_u64 v[182:183], s[24:25], 0, v[156:157]
	s_add_i32 m0, s19, 0xc000
	ds_read_b128 v[178:181], v169
	ds_read_b128 v[186:189], v169 offset:1024
	ds_read_b128 v[196:199], v169 offset:2048
	ds_read_b128 v[200:203], v169 offset:3072
	ds_read_b128 v[204:207], v169 offset:4096
	ds_read_b128 v[208:211], v169 offset:5120
	ds_read_b128 v[212:215], v169 offset:6144
	ds_read_b128 v[216:219], v169 offset:7168
	global_load_lds_dwordx4 v[182:183], off
	v_lshl_add_u64 v[182:183], s[24:25], 0, v[158:159]
	s_add_i32 m0, s19, 0xe000
	s_nop 0
	global_load_lds_dwordx4 v[182:183], off
	s_waitcnt vmcnt(8)
	s_waitcnt lgkmcnt(0)
	s_barrier
	s_setprio 1
	s_waitcnt lgkmcnt(0)
	v_mfma_f32_16x16x32_bf16 v[146:149], v[94:97], v[178:181], v[146:149]
	v_mfma_f32_16x16x32_bf16 v[146:149], v[98:101], v[186:189], v[146:149]
	v_mfma_f32_16x16x32_bf16 v[142:145], v[102:105], v[178:181], v[142:145]
	v_mfma_f32_16x16x32_bf16 v[142:145], v[106:109], v[186:189], v[142:145]
	v_mfma_f32_16x16x32_bf16 v[130:133], v[94:97], v[196:199], v[130:133]
	v_mfma_f32_16x16x32_bf16 v[130:133], v[98:101], v[200:203], v[130:133]
	v_mfma_f32_16x16x32_bf16 v[126:129], v[102:105], v[196:199], v[126:129]
	v_mfma_f32_16x16x32_bf16 v[126:129], v[106:109], v[200:203], v[126:129]
	v_mfma_f32_16x16x32_bf16 v[114:117], v[94:97], v[204:207], v[114:117]
	v_mfma_f32_16x16x32_bf16 v[114:117], v[98:101], v[208:211], v[114:117]
	v_mfma_f32_16x16x32_bf16 v[110:113], v[102:105], v[204:207], v[110:113]
	v_mfma_f32_16x16x32_bf16 v[110:113], v[106:109], v[208:211], v[110:113]
	v_mfma_f32_16x16x32_bf16 v[82:85], v[94:97], v[212:215], v[82:85]
	v_mfma_f32_16x16x32_bf16 v[82:85], v[98:101], v[216:219], v[82:85]
	v_mfma_f32_16x16x32_bf16 v[78:81], v[102:105], v[212:215], v[78:81]
	v_mfma_f32_16x16x32_bf16 v[78:81], v[106:109], v[216:219], v[78:81]
	s_setprio 0
	s_setprio 1
	v_mfma_f32_16x16x32_bf16 v[138:141], v[160:163], v[178:181], v[138:141]
	v_mfma_f32_16x16x32_bf16 v[138:141], v[164:167], v[186:189], v[138:141]
	v_mfma_f32_16x16x32_bf16 v[134:137], v[170:173], v[178:181], v[134:137]
	v_mfma_f32_16x16x32_bf16 v[134:137], v[174:177], v[186:189], v[134:137]
	v_mfma_f32_16x16x32_bf16 v[122:125], v[160:163], v[196:199], v[122:125]
	v_mfma_f32_16x16x32_bf16 v[122:125], v[164:167], v[200:203], v[122:125]
	v_mfma_f32_16x16x32_bf16 v[118:121], v[170:173], v[196:199], v[118:121]
	v_mfma_f32_16x16x32_bf16 v[118:121], v[174:177], v[200:203], v[118:121]
	v_mfma_f32_16x16x32_bf16 v[90:93], v[160:163], v[204:207], v[90:93]
	v_mfma_f32_16x16x32_bf16 v[90:93], v[164:167], v[208:211], v[90:93]
	v_mfma_f32_16x16x32_bf16 v[86:89], v[170:173], v[204:207], v[86:89]
	v_mfma_f32_16x16x32_bf16 v[86:89], v[174:177], v[208:211], v[86:89]
	v_mfma_f32_16x16x32_bf16 v[74:77], v[160:163], v[212:215], v[74:77]
	v_mfma_f32_16x16x32_bf16 v[74:77], v[164:167], v[216:219], v[74:77]
	v_mfma_f32_16x16x32_bf16 v[70:73], v[170:173], v[212:215], v[70:73]
	v_mfma_f32_16x16x32_bf16 v[70:73], v[174:177], v[216:219], v[70:73]
	s_setprio 0
	s_barrier
	s_add_i32 s42, s42, s30
	v_lshl_add_u64 v[182:183], s[26:27], 0, v[32:33]
	s_mov_b32 m0, s42
	ds_read_b128 v[178:181], v169 offset:16384
	ds_read_b128 v[186:189], v169 offset:17408
	ds_read_b128 v[196:199], v169 offset:18432
	ds_read_b128 v[200:203], v169 offset:19456
	ds_read_b128 v[204:207], v169 offset:20480
	ds_read_b128 v[208:211], v169 offset:21504
	ds_read_b128 v[212:215], v169 offset:22528
	ds_read_b128 v[216:219], v169 offset:23552
	global_load_lds_dwordx4 v[182:183], off
	s_add_i32 m0, s42, 0x2000
	s_add_u32 s42, s26, 0x80000
	v_lshl_add_u64 v[190:191], s[26:27], 0, v[154:155]
	s_addc_u32 s43, s27, 0
	s_add_i32 s46, s46, s30
	global_load_lds_dwordx4 v[190:191], off
	v_lshl_add_u64 v[220:221], s[42:43], 0, v[32:33]
	s_mov_b32 m0, s46
	v_lshl_add_u64 v[222:223], s[28:29], 0, v[152:153]
	global_load_lds_dwordx4 v[220:221], off
	v_lshl_add_u64 v[220:221], s[42:43], 0, v[154:155]
	s_add_i32 m0, s46, 0x2000
	s_nop 0
	global_load_lds_dwordx4 v[220:221], off
	v_lshl_add_u64 v[220:221], s[28:29], 0, v[150:151]
	s_mov_b32 m0, s19
	s_nop 0
	global_load_lds_dwordx4 v[220:221], off
	s_mov_b32 m0, s23
	s_nop 0
	global_load_lds_dwordx4 v[222:223], off
	s_waitcnt vmcnt(8)
	s_waitcnt lgkmcnt(0)
	s_barrier
; #define PG8_STAGE(bufoff, gbase, voff) do { _Pragma("unroll") for (int _i = 0; _i < 2; ++_i) \
;         __builtin_amdgcn_global_load_lds((const unsigned*)((const char*)(gbase) + (voff)[_i]), (PG8_LAS unsigned*)(lds + (bufoff) + ldsw + _i * 8192), 16, 0, 0); } while (0)
; #define PG8_LDA(dst, b, h) do { _Pragma("unroll") for (int m = 0; m < 4; ++m) _Pragma("unroll") for (int k = 0; k < 2; ++k) dst[m][k] = *(const PG8_LAS bf16x8*)(lds + PG8_SA(b, h) + aoff + m * 2048 + k * 1024); } while (0)
; #define PG8_LDB(dst, b, h) do { _Pragma("unroll") for (int n = 0; n < 2; ++n) _Pragma("unroll") for (int k = 0; k < 2; ++k) dst[n][k] = *(const PG8_LAS bf16x8*)(lds + PG8_SB(b, h) + boff + n * 2048 + k * 1024); } while (0)
; #define PG8_MMA(ai, bj, At, Bt) do { __builtin_amdgcn_s_setprio(1); _Pragma("unroll") for (int m = 0; m < 4; ++m) _Pragma("unroll") for (int n = 0; n < 2; ++n) _Pragma("unroll") for (int k = 0; k < 2; ++k) \
;         acc[ai][bj][m][n] = __builtin_amdgcn_mfma_f32_16x16x32_bf16(Bt[n][k], At[m][k], acc[ai][bj][m][n], 0, 0, 0); __builtin_amdgcn_s_setprio(0); } while (0)
; #define PG8_WAIT_V(n) asm volatile("s_waitcnt vmcnt(" #n ")" ::: "memory")
; #define PG8_WAIT_L(n) asm volatile("s_waitcnt lgkmcnt(" #n ")" ::: "memory")
; #define PG8_BAR __builtin_amdgcn_s_barrier()
; #define PG8_SCHED __builtin_amdgcn_sched_barrier(0)
;     ...
;             PG8_WAIT_V(8); PG8_WAIT_L(0); PG8_BAR; PG8_MMA(1, 0, At, B0); PG8_MMA(1, 1, At, B1); PG8_BAR; PG8_SCHED;
;             PG8_LDB(B0, 1, 0); PG8_LDB(B1, 1, 1); PG8_SCHED; PG8_LDA(At, 1, 0); PG8_STAGE(PG8_SA(0, 1), a2 + hstepA, voffA);
;             PG8_WAIT_V(8); PG8_WAIT_L(0); PG8_BAR; PG8_MMA(0, 0, At, B0); PG8_MMA(0, 1, At, B1); PG8_BAR; PG8_SCHED;
	s_setprio 1
	s_waitcnt lgkmcnt(0)
	v_mfma_f32_16x16x32_bf16 v[66:69], v[94:97], v[178:181], v[66:69]
	v_mfma_f32_16x16x32_bf16 v[66:69], v[98:101], v[186:189], v[66:69]
	v_mfma_f32_16x16x32_bf16 v[62:65], v[102:105], v[178:181], v[62:65]
	v_mfma_f32_16x16x32_bf16 v[62:65], v[106:109], v[186:189], v[62:65]
	v_mfma_f32_16x16x32_bf16 v[50:53], v[94:97], v[196:199], v[50:53]
	v_mfma_f32_16x16x32_bf16 v[50:53], v[98:101], v[200:203], v[50:53]
	v_mfma_f32_16x16x32_bf16 v[46:49], v[102:105], v[196:199], v[46:49]
	v_mfma_f32_16x16x32_bf16 v[46:49], v[106:109], v[200:203], v[46:49]
	v_mfma_f32_16x16x32_bf16 v[34:37], v[94:97], v[204:207], v[34:37]
	v_mfma_f32_16x16x32_bf16 v[34:37], v[98:101], v[208:211], v[34:37]
	v_mfma_f32_16x16x32_bf16 v[26:29], v[102:105], v[204:207], v[26:29]
	v_mfma_f32_16x16x32_bf16 v[26:29], v[106:109], v[208:211], v[26:29]
	v_mfma_f32_16x16x32_bf16 v[14:17], v[94:97], v[212:215], v[14:17]
	v_mfma_f32_16x16x32_bf16 v[14:17], v[98:101], v[216:219], v[14:17]
	v_mfma_f32_16x16x32_bf16 v[10:13], v[102:105], v[212:215], v[10:13]
	v_mfma_f32_16x16x32_bf16 v[10:13], v[106:109], v[216:219], v[10:13]
	s_setprio 0
	s_setprio 1
	v_mfma_f32_16x16x32_bf16 v[58:61], v[160:163], v[178:181], v[58:61]
	v_mfma_f32_16x16x32_bf16 v[58:61], v[164:167], v[186:189], v[58:61]
	v_mfma_f32_16x16x32_bf16 v[54:57], v[170:173], v[178:181], v[54:57]
	v_mfma_f32_16x16x32_bf16 v[54:57], v[174:177], v[186:189], v[54:57]
	v_mfma_f32_16x16x32_bf16 v[42:45], v[160:163], v[196:199], v[42:45]
	v_mfma_f32_16x16x32_bf16 v[42:45], v[164:167], v[200:203], v[42:45]
	v_mfma_f32_16x16x32_bf16 v[38:41], v[170:173], v[196:199], v[38:41]
	v_mfma_f32_16x16x32_bf16 v[38:41], v[174:177], v[200:203], v[38:41]
	v_mfma_f32_16x16x32_bf16 v[22:25], v[160:163], v[204:207], v[22:25]
	v_mfma_f32_16x16x32_bf16 v[22:25], v[164:167], v[208:211], v[22:25]
	v_mfma_f32_16x16x32_bf16 v[18:21], v[170:173], v[204:207], v[18:21]
	v_mfma_f32_16x16x32_bf16 v[18:21], v[174:177], v[208:211], v[18:21]
	v_mfma_f32_16x16x32_bf16 v[6:9], v[160:163], v[212:215], v[6:9]
	v_mfma_f32_16x16x32_bf16 v[6:9], v[164:167], v[216:219], v[6:9]
	v_mfma_f32_16x16x32_bf16 v[2:5], v[170:173], v[212:215], v[2:5]
	v_mfma_f32_16x16x32_bf16 v[2:5], v[174:177], v[216:219], v[2:5]
	s_setprio 0
	s_barrier
	s_add_i32 s42, 0, 0x18000
	s_add_i32 s43, 0, 0x1c000
	v_add_u32_e32 v106, s42, v31
	v_add_u32_e32 v174, s43, v31
	ds_read_b128 v[94:97], v106
	ds_read_b128 v[98:101], v106 offset:1024
	ds_read_b128 v[102:105], v106 offset:2048
	ds_read_b128 v[106:109], v106 offset:3072
	ds_read_b128 v[160:163], v174
	ds_read_b128 v[164:167], v174 offset:1024
	ds_read_b128 v[170:173], v174 offset:2048
	ds_read_b128 v[174:177], v174 offset:3072
	s_add_u32 s28, s28, 0x80000
	s_addc_u32 s29, s29, 0
	s_mov_b32 m0, s31
	v_lshl_add_u64 v[224:225], s[28:29], 0, v[150:151]
	ds_read_b128 v[178:181], v169 offset:32768
	ds_read_b128 v[186:189], v169 offset:33792
	ds_read_b128 v[196:199], v169 offset:34816
	ds_read_b128 v[200:203], v169 offset:35840
	ds_read_b128 v[204:207], v169 offset:36864
	ds_read_b128 v[208:211], v169 offset:37888
	ds_read_b128 v[212:215], v169 offset:38912
	ds_read_b128 v[216:219], v169 offset:39936
	global_load_lds_dwordx4 v[224:225], off
	v_lshl_add_u64 v[224:225], s[28:29], 0, v[152:153]
	s_mov_b32 m0, s38
	s_nop 0
	global_load_lds_dwordx4 v[224:225], off
	s_waitcnt vmcnt(8)
	s_waitcnt lgkmcnt(0)
	s_barrier
	s_setprio 1
	s_waitcnt lgkmcnt(0)
	v_mfma_f32_16x16x32_bf16 v[146:149], v[94:97], v[178:181], v[146:149]
	v_mfma_f32_16x16x32_bf16 v[146:149], v[98:101], v[186:189], v[146:149]
	v_mfma_f32_16x16x32_bf16 v[142:145], v[102:105], v[178:181], v[142:145]
	v_mfma_f32_16x16x32_bf16 v[142:145], v[106:109], v[186:189], v[142:145]
	v_mfma_f32_16x16x32_bf16 v[130:133], v[94:97], v[196:199], v[130:133]
	v_mfma_f32_16x16x32_bf16 v[130:133], v[98:101], v[200:203], v[130:133]
	v_mfma_f32_16x16x32_bf16 v[126:129], v[102:105], v[196:199], v[126:129]
	v_mfma_f32_16x16x32_bf16 v[126:129], v[106:109], v[200:203], v[126:129]
	v_mfma_f32_16x16x32_bf16 v[114:117], v[94:97], v[204:207], v[114:117]
	v_mfma_f32_16x16x32_bf16 v[114:117], v[98:101], v[208:211], v[114:117]
	v_mfma_f32_16x16x32_bf16 v[110:113], v[102:105], v[204:207], v[110:113]
	v_mfma_f32_16x16x32_bf16 v[110:113], v[106:109], v[208:211], v[110:113]
	v_mfma_f32_16x16x32_bf16 v[82:85], v[94:97], v[212:215], v[82:85]
	v_mfma_f32_16x16x32_bf16 v[82:85], v[98:101], v[216:219], v[82:85]
	v_mfma_f32_16x16x32_bf16 v[78:81], v[102:105], v[212:215], v[78:81]
	v_mfma_f32_16x16x32_bf16 v[78:81], v[106:109], v[216:219], v[78:81]
	s_setprio 0
	s_setprio 1
	v_mfma_f32_16x16x32_bf16 v[138:141], v[160:163], v[178:181], v[138:141]
	v_mfma_f32_16x16x32_bf16 v[138:141], v[164:167], v[186:189], v[138:141]
	v_mfma_f32_16x16x32_bf16 v[134:137], v[170:173], v[178:181], v[134:137]
	v_mfma_f32_16x16x32_bf16 v[134:137], v[174:177], v[186:189], v[134:137]
	v_mfma_f32_16x16x32_bf16 v[122:125], v[160:163], v[196:199], v[122:125]
	v_mfma_f32_16x16x32_bf16 v[122:125], v[164:167], v[200:203], v[122:125]
	v_mfma_f32_16x16x32_bf16 v[118:121], v[170:173], v[196:199], v[118:121]
	v_mfma_f32_16x16x32_bf16 v[118:121], v[174:177], v[200:203], v[118:121]
	v_mfma_f32_16x16x32_bf16 v[90:93], v[160:163], v[204:207], v[90:93]
	v_mfma_f32_16x16x32_bf16 v[90:93], v[164:167], v[208:211], v[90:93]
	v_mfma_f32_16x16x32_bf16 v[86:89], v[170:173], v[204:207], v[86:89]
	v_mfma_f32_16x16x32_bf16 v[86:89], v[174:177], v[208:211], v[86:89]
	v_mfma_f32_16x16x32_bf16 v[74:77], v[160:163], v[212:215], v[74:77]
	v_mfma_f32_16x16x32_bf16 v[74:77], v[164:167], v[216:219], v[74:77]
	v_mfma_f32_16x16x32_bf16 v[70:73], v[170:173], v[212:215], v[70:73]
	v_mfma_f32_16x16x32_bf16 v[70:73], v[174:177], v[216:219], v[70:73]
	s_setprio 0
	s_barrier
; #define PG8_STAGE(bufoff, gbase, voff) do { _Pragma("unroll") for (int _i = 0; _i < 2; ++_i) \
;         __builtin_amdgcn_global_load_lds((const unsigned*)((const char*)(gbase) + (voff)[_i]), (PG8_LAS unsigned*)(lds + (bufoff) + ldsw + _i * 8192), 16, 0, 0); } while (0)
; #define PG8_LDA(dst, b, h) do { _Pragma("unroll") for (int m = 0; m < 4; ++m) _Pragma("unroll") for (int k = 0; k < 2; ++k) dst[m][k] = *(const PG8_LAS bf16x8*)(lds + PG8_SA(b, h) + aoff + m * 2048 + k * 1024); } while (0)
; #define PG8_MMA(ai, bj, At, Bt) do { __builtin_amdgcn_s_setprio(1); _Pragma("unroll") for (int m = 0; m < 4; ++m) _Pragma("unroll") for (int n = 0; n < 2; ++n) _Pragma("unroll") for (int k = 0; k < 2; ++k) \
;         acc[ai][bj][m][n] = __builtin_amdgcn_mfma_f32_16x16x32_bf16(Bt[n][k], At[m][k], acc[ai][bj][m][n], 0, 0, 0); __builtin_amdgcn_s_setprio(0); } while (0)
; #define PG8_WAIT_V(n) asm volatile("s_waitcnt vmcnt(" #n ")" ::: "memory")
; #define PG8_WAIT_L(n) asm volatile("s_waitcnt lgkmcnt(" #n ")" ::: "memory")
; #define PG8_BAR __builtin_amdgcn_s_barrier()
; #define PG8_SCHED __builtin_amdgcn_sched_barrier(0)
;     ...
;         for (int t = 0; t < nt; t += 2) {
;             const bool last = (t == nt - 2);
;             const char* a1 = cA + (size_t)(t + 1) * kstep;
;             const char* a2 = last ? nA : cA + (size_t)(t + 2) * kstep; const char* b2 = last ? nB : cB + (size_t)(t + 2) * kstep;
;     ...
;             PG8_LDA(At, 1, 1); PG8_STAGE(PG8_SB(1, 0), b3, voffB); PG8_STAGE(PG8_SB(1, 1), b3 + hstep, voffB); PG8_STAGE(PG8_SA(1, 0), a3, voffA);
;             PG8_WAIT_V(8); PG8_WAIT_L(0); PG8_BAR; PG8_MMA(1, 0, At, B0); PG8_MMA(1, 1, At, B1); PG8_BAR; PG8_SCHED;
	s_add_i32 s28, s42, s30
	v_lshl_add_u64 v[182:183], v[182:183], 0, s[64:65]
	s_mov_b32 m0, s28
	ds_read_b128 v[178:181], v169 offset:49152
	ds_read_b128 v[186:189], v169 offset:50176
	ds_read_b128 v[196:199], v169 offset:51200
	ds_read_b128 v[200:203], v169 offset:52224
	ds_read_b128 v[204:207], v169 offset:53248
	ds_read_b128 v[208:211], v169 offset:54272
	ds_read_b128 v[212:215], v169 offset:55296
	ds_read_b128 v[216:219], v169 offset:56320
	global_load_lds_dwordx4 v[182:183], off
	s_add_i32 m0, s28, 0x2000
	s_add_u32 s26, s26, 0x80080
	v_lshl_add_u64 v[182:183], v[190:191], 0, s[64:65]
	s_addc_u32 s27, s27, 0
	s_add_i32 s28, s43, s30
	global_load_lds_dwordx4 v[182:183], off
	v_lshl_add_u64 v[182:183], s[26:27], 0, v[32:33]
	s_mov_b32 m0, s28
	s_nop 0
	global_load_lds_dwordx4 v[182:183], off
	v_lshl_add_u64 v[182:183], s[26:27], 0, v[154:155]
	s_add_i32 m0, s28, 0x2000
	s_nop 0
	global_load_lds_dwordx4 v[182:183], off
	v_lshl_add_u64 v[182:183], v[220:221], 0, s[64:65]
	s_mov_b32 m0, s41
	s_nop 0
	global_load_lds_dwordx4 v[182:183], off
	v_lshl_add_u64 v[182:183], v[222:223], 0, s[64:65]
	s_mov_b32 m0, s50
	s_nop 0
	global_load_lds_dwordx4 v[182:183], off
	s_waitcnt vmcnt(8)
	s_waitcnt lgkmcnt(0)
	s_barrier
	s_setprio 1
	s_waitcnt lgkmcnt(0)
	v_mfma_f32_16x16x32_bf16 v[66:69], v[94:97], v[178:181], v[66:69]
	v_mfma_f32_16x16x32_bf16 v[66:69], v[98:101], v[186:189], v[66:69]
	v_mfma_f32_16x16x32_bf16 v[62:65], v[102:105], v[178:181], v[62:65]
	v_mfma_f32_16x16x32_bf16 v[62:65], v[106:109], v[186:189], v[62:65]
	v_mfma_f32_16x16x32_bf16 v[50:53], v[94:97], v[196:199], v[50:53]
	v_mfma_f32_16x16x32_bf16 v[50:53], v[98:101], v[200:203], v[50:53]
	v_mfma_f32_16x16x32_bf16 v[46:49], v[102:105], v[196:199], v[46:49]
	v_mfma_f32_16x16x32_bf16 v[46:49], v[106:109], v[200:203], v[46:49]
	v_mfma_f32_16x16x32_bf16 v[34:37], v[94:97], v[204:207], v[34:37]
	v_mfma_f32_16x16x32_bf16 v[34:37], v[98:101], v[208:211], v[34:37]
	v_mfma_f32_16x16x32_bf16 v[26:29], v[102:105], v[204:207], v[26:29]
	v_mfma_f32_16x16x32_bf16 v[26:29], v[106:109], v[208:211], v[26:29]
	v_mfma_f32_16x16x32_bf16 v[14:17], v[94:97], v[212:215], v[14:17]
	v_mfma_f32_16x16x32_bf16 v[14:17], v[98:101], v[216:219], v[14:17]
	v_mfma_f32_16x16x32_bf16 v[10:13], v[102:105], v[212:215], v[10:13]
	v_mfma_f32_16x16x32_bf16 v[10:13], v[106:109], v[216:219], v[10:13]
	s_setprio 0
	s_setprio 1
	v_mfma_f32_16x16x32_bf16 v[58:61], v[160:163], v[178:181], v[58:61]
	v_mfma_f32_16x16x32_bf16 v[58:61], v[164:167], v[186:189], v[58:61]
	v_mfma_f32_16x16x32_bf16 v[54:57], v[170:173], v[178:181], v[54:57]
	v_mfma_f32_16x16x32_bf16 v[54:57], v[174:177], v[186:189], v[54:57]
	v_mfma_f32_16x16x32_bf16 v[42:45], v[160:163], v[196:199], v[42:45]
	v_mfma_f32_16x16x32_bf16 v[42:45], v[164:167], v[200:203], v[42:45]
	v_mfma_f32_16x16x32_bf16 v[38:41], v[170:173], v[196:199], v[38:41]
	v_mfma_f32_16x16x32_bf16 v[38:41], v[174:177], v[200:203], v[38:41]
	v_mfma_f32_16x16x32_bf16 v[22:25], v[160:163], v[204:207], v[22:25]
	v_mfma_f32_16x16x32_bf16 v[22:25], v[164:167], v[208:211], v[22:25]
	v_mfma_f32_16x16x32_bf16 v[18:21], v[170:173], v[204:207], v[18:21]
	v_mfma_f32_16x16x32_bf16 v[18:21], v[174:177], v[208:211], v[18:21]
	v_mfma_f32_16x16x32_bf16 v[6:9], v[160:163], v[212:215], v[6:9]
	v_mfma_f32_16x16x32_bf16 v[6:9], v[164:167], v[216:219], v[6:9]
	v_mfma_f32_16x16x32_bf16 v[2:5], v[170:173], v[212:215], v[2:5]
	v_mfma_f32_16x16x32_bf16 v[2:5], v[174:177], v[216:219], v[2:5]
	s_setprio 0
	s_barrier
	s_add_i32 s79, s79, 2
	s_add_u32 s24, s24, 0x100
	s_addc_u32 s25, s25, 0
	s_add_u32 s74, s74, 0x100
	s_addc_u32 s78, s78, 0
	s_cmp_gt_u32 s79, 29
	s_cbranch_scc0 .LBB0_1332
	s_and_b64 vcc, exec, s[6:7]
	s_cbranch_vccz .LBB0_1335
	s_barrier

; #define PG8_STAGE(bufoff, gbase, voff) do { _Pragma("unroll") for (int _i = 0; _i < 2; ++_i) \
;         __builtin_amdgcn_global_load_lds((const unsigned*)((const char*)(gbase) + (voff)[_i]), (PG8_LAS unsigned*)(lds + (bufoff) + ldsw + _i * 8192), 16, 0, 0); } while (0)
; #define PG8_LDA(dst, b, h) do { _Pragma("unroll") for (int m = 0; m < 4; ++m) _Pragma("unroll") for (int k = 0; k < 2; ++k) dst[m][k] = *(const PG8_LAS bf16x8*)(lds + PG8_SA(b, h) + aoff + m * 2048 + k * 1024); } while (0)
; #define PG8_LDB(dst, b, h) do { _Pragma("unroll") for (int n = 0; n < 2; ++n) _Pragma("unroll") for (int k = 0; k < 2; ++k) dst[n][k] = *(const PG8_LAS bf16x8*)(lds + PG8_SB(b, h) + boff + n * 2048 + k * 1024); } while (0)
; #define PG8_MMA(ai, bj, At, Bt) do { __builtin_amdgcn_s_setprio(1); _Pragma("unroll") for (int m = 0; m < 4; ++m) _Pragma("unroll") for (int n = 0; n < 2; ++n) _Pragma("unroll") for (int k = 0; k < 2; ++k) \
;         acc[ai][bj][m][n] = __builtin_amdgcn_mfma_f32_16x16x32_bf16(Bt[n][k], At[m][k], acc[ai][bj][m][n], 0, 0, 0); __builtin_amdgcn_s_setprio(0); } while (0)
; #define PG8_WAIT_V(n) asm volatile("s_waitcnt vmcnt(" #n ")" ::: "memory")
; #define PG8_WAIT_L(n) asm volatile("s_waitcnt lgkmcnt(" #n ")" ::: "memory")
; #define PG8_BAR __builtin_amdgcn_s_barrier()
; #define PG8_SCHED __builtin_amdgcn_sched_barrier(0)
;     ...
;             const bool last = (t == nt - 2);
;             const char* a1 = cA + (size_t)(t + 1) * kstep;
;             const char* a2 = last ? nA : cA + (size_t)(t + 2) * kstep; const char* b2 = last ? nB : cB + (size_t)(t + 2) * kstep;
;             const char* a3 = a2 + kstep; const char* b3 = b2 + kstep;
;             if (last && has_next) S.a_ready(nxt);
;             if constexpr (SP2) {
;             PG8_LDB(B0, 0, 0); PG8_LDB(B1, 0, 1); PG8_SCHED; PG8_LDA(At, 0, 0); PG8_STAGE(PG8_SA(1, 1), a1 + hstepA, voffA);
;             PG8_WAIT_V(8); PG8_WAIT_L(0); PG8_BAR; PG8_MMA(0, 0, At, B0); PG8_MMA(0, 1, At, B1); PG8_BAR; PG8_SCHED;
;             PG8_LDA(At, 0, 1); PG8_STAGE(PG8_SB(0, 0), b2, voffB); PG8_STAGE(PG8_SB(0, 1), b2 + hstep, voffB); PG8_STAGE(PG8_SA(0, 0), a2, voffA);
;             PG8_WAIT_V(8); PG8_WAIT_L(0); PG8_BAR; PG8_MMA(1, 0, At, B0); PG8_MMA(1, 1, At, B1); PG8_BAR; PG8_SCHED;
.LBB0_1454:
	s_add_u32 s30, s28, 0x100
	s_addc_u32 s31, s29, 0
	s_add_i32 s27, 0, 0x10000
	s_cmp_eq_u32 s40, s25
	s_cselect_b32 s93, s95, s31
	s_cselect_b32 s92, s94, s30
	v_add_u32_e32 v32, s27, v239
	s_cselect_b32 s39, s97, s23
	s_cselect_b32 s38, s96, s9
	s_add_i32 s33, 0, 0x14000
	ds_read_b128 v[72:75], v32
	ds_read_b128 v[76:79], v32 offset:1024
	ds_read_b128 v[80:83], v32 offset:2048
	ds_read_b128 v[88:91], v32 offset:3072
	v_add_u32_e32 v32, s33, v239
	ds_read_b128 v[152:155], v32
	ds_read_b128 v[156:159], v32 offset:1024
	ds_read_b128 v[160:163], v32 offset:2048
	ds_read_b128 v[164:167], v32 offset:3072
	v_lshl_add_u64 v[34:35], s[28:29], 0, v[196:197]
	s_add_i32 m0, s4, 0xc000
	ds_read_b128 v[168:171], v251
	ds_read_b128 v[172:175], v251 offset:1024
	ds_read_b128 v[176:179], v251 offset:2048
	ds_read_b128 v[186:189], v251 offset:3072
	ds_read_b128 v[200:203], v251 offset:4096
	ds_read_b128 v[204:207], v251 offset:5120
	ds_read_b128 v[208:211], v251 offset:6144
	ds_read_b128 v[212:215], v251 offset:7168
	global_load_lds_dwordx4 v[34:35], off
	v_lshl_add_u64 v[34:35], s[28:29], 0, v[198:199]
	s_add_i32 m0, s4, 0xe000
	s_nop 0
	global_load_lds_dwordx4 v[34:35], off
	s_waitcnt vmcnt(8)
	s_waitcnt lgkmcnt(0)
	s_barrier
	s_setprio 1
	s_waitcnt lgkmcnt(0)
	v_mfma_f32_16x16x32_bf16 v[84:87], v[72:75], v[168:171], v[84:87]
	v_mfma_f32_16x16x32_bf16 v[84:87], v[76:79], v[172:175], v[84:87]
	v_mfma_f32_16x16x32_bf16 v[148:151], v[80:83], v[168:171], v[148:151]
	v_mfma_f32_16x16x32_bf16 v[148:151], v[88:91], v[172:175], v[148:151]
	v_mfma_f32_16x16x32_bf16 v[136:139], v[72:75], v[176:179], v[136:139]
	v_mfma_f32_16x16x32_bf16 v[136:139], v[76:79], v[186:189], v[136:139]
	v_mfma_f32_16x16x32_bf16 v[132:135], v[80:83], v[176:179], v[132:135]
	v_mfma_f32_16x16x32_bf16 v[132:135], v[88:91], v[186:189], v[132:135]
	v_mfma_f32_16x16x32_bf16 v[120:123], v[72:75], v[200:203], v[120:123]
	v_mfma_f32_16x16x32_bf16 v[120:123], v[76:79], v[204:207], v[120:123]
	v_mfma_f32_16x16x32_bf16 v[116:119], v[80:83], v[200:203], v[116:119]
	v_mfma_f32_16x16x32_bf16 v[116:119], v[88:91], v[204:207], v[116:119]
	v_mfma_f32_16x16x32_bf16 v[104:107], v[72:75], v[208:211], v[104:107]
	v_mfma_f32_16x16x32_bf16 v[104:107], v[76:79], v[212:215], v[104:107]
	v_mfma_f32_16x16x32_bf16 v[100:103], v[80:83], v[208:211], v[100:103]
	v_mfma_f32_16x16x32_bf16 v[100:103], v[88:91], v[212:215], v[100:103]
	s_setprio 0
	s_setprio 1
	v_mfma_f32_16x16x32_bf16 v[144:147], v[152:155], v[168:171], v[144:147]
	v_mfma_f32_16x16x32_bf16 v[144:147], v[156:159], v[172:175], v[144:147]
	v_mfma_f32_16x16x32_bf16 v[140:143], v[160:163], v[168:171], v[140:143]
	v_mfma_f32_16x16x32_bf16 v[140:143], v[164:167], v[172:175], v[140:143]
	v_mfma_f32_16x16x32_bf16 v[128:131], v[152:155], v[176:179], v[128:131]
	v_mfma_f32_16x16x32_bf16 v[128:131], v[156:159], v[186:189], v[128:131]
	v_mfma_f32_16x16x32_bf16 v[124:127], v[160:163], v[176:179], v[124:127]
	v_mfma_f32_16x16x32_bf16 v[124:127], v[164:167], v[186:189], v[124:127]
	v_mfma_f32_16x16x32_bf16 v[112:115], v[152:155], v[200:203], v[112:115]
	v_mfma_f32_16x16x32_bf16 v[112:115], v[156:159], v[204:207], v[112:115]
	v_mfma_f32_16x16x32_bf16 v[108:111], v[160:163], v[200:203], v[108:111]
	v_mfma_f32_16x16x32_bf16 v[108:111], v[164:167], v[204:207], v[108:111]
	v_mfma_f32_16x16x32_bf16 v[96:99], v[152:155], v[208:211], v[96:99]
	v_mfma_f32_16x16x32_bf16 v[96:99], v[156:159], v[212:215], v[96:99]
	v_mfma_f32_16x16x32_bf16 v[92:95], v[160:163], v[208:211], v[92:95]
	v_mfma_f32_16x16x32_bf16 v[92:95], v[164:167], v[212:215], v[92:95]
	s_setprio 0
	s_barrier
	s_add_i32 s27, s27, s3
	v_lshl_add_u64 v[190:191], s[38:39], 0, v[30:31]
	s_mov_b32 m0, s27
	ds_read_b128 v[168:171], v251 offset:16384
	ds_read_b128 v[172:175], v251 offset:17408
	ds_read_b128 v[176:179], v251 offset:18432
	ds_read_b128 v[186:189], v251 offset:19456
	ds_read_b128 v[200:203], v251 offset:20480
	ds_read_b128 v[204:207], v251 offset:21504
	ds_read_b128 v[208:211], v251 offset:22528
	ds_read_b128 v[212:215], v251 offset:23552
	global_load_lds_dwordx4 v[190:191], off
	s_add_i32 m0, s27, 0x2000
	s_add_u32 s28, s38, 0x200000
	v_lshl_add_u64 v[216:217], s[38:39], 0, v[180:181]
	s_addc_u32 s29, s39, 0
	s_add_i32 s27, s33, s3
	global_load_lds_dwordx4 v[216:217], off
	v_lshl_add_u64 v[34:35], s[28:29], 0, v[30:31]
	s_mov_b32 m0, s27
	v_lshl_add_u64 v[218:219], s[92:93], 0, v[30:31]
	global_load_lds_dwordx4 v[34:35], off
	v_lshl_add_u64 v[34:35], s[28:29], 0, v[180:181]
	s_add_i32 m0, s27, 0x2000
	v_lshl_add_u64 v[220:221], s[92:93], 0, v[180:181]
	global_load_lds_dwordx4 v[34:35], off
	s_mov_b32 m0, s4
	s_nop 0
	global_load_lds_dwordx4 v[218:219], off
	s_mov_b32 m0, s5
	s_nop 0
	global_load_lds_dwordx4 v[220:221], off
	s_waitcnt vmcnt(8)
	s_waitcnt lgkmcnt(0)
	s_barrier
; #define PG8_STAGE(bufoff, gbase, voff) do { _Pragma("unroll") for (int _i = 0; _i < 2; ++_i) \
;         __builtin_amdgcn_global_load_lds((const unsigned*)((const char*)(gbase) + (voff)[_i]), (PG8_LAS unsigned*)(lds + (bufoff) + ldsw + _i * 8192), 16, 0, 0); } while (0)
; #define PG8_LDA(dst, b, h) do { _Pragma("unroll") for (int m = 0; m < 4; ++m) _Pragma("unroll") for (int k = 0; k < 2; ++k) dst[m][k] = *(const PG8_LAS bf16x8*)(lds + PG8_SA(b, h) + aoff + m * 2048 + k * 1024); } while (0)
; #define PG8_LDB(dst, b, h) do { _Pragma("unroll") for (int n = 0; n < 2; ++n) _Pragma("unroll") for (int k = 0; k < 2; ++k) dst[n][k] = *(const PG8_LAS bf16x8*)(lds + PG8_SB(b, h) + boff + n * 2048 + k * 1024); } while (0)
; #define PG8_MMA(ai, bj, At, Bt) do { __builtin_amdgcn_s_setprio(1); _Pragma("unroll") for (int m = 0; m < 4; ++m) _Pragma("unroll") for (int n = 0; n < 2; ++n) _Pragma("unroll") for (int k = 0; k < 2; ++k) \
;         acc[ai][bj][m][n] = __builtin_amdgcn_mfma_f32_16x16x32_bf16(Bt[n][k], At[m][k], acc[ai][bj][m][n], 0, 0, 0); __builtin_amdgcn_s_setprio(0); } while (0)
; #define PG8_WAIT_V(n) asm volatile("s_waitcnt vmcnt(" #n ")" ::: "memory")
; #define PG8_WAIT_L(n) asm volatile("s_waitcnt lgkmcnt(" #n ")" ::: "memory")
; #define PG8_BAR __builtin_amdgcn_s_barrier()
; #define PG8_SCHED __builtin_amdgcn_sched_barrier(0)
;     ...
;             PG8_WAIT_V(8); PG8_WAIT_L(0); PG8_BAR; PG8_MMA(1, 0, At, B0); PG8_MMA(1, 1, At, B1); PG8_BAR; PG8_SCHED;
;             PG8_LDB(B0, 1, 0); PG8_LDB(B1, 1, 1); PG8_SCHED; PG8_LDA(At, 1, 0); PG8_STAGE(PG8_SA(0, 1), a2 + hstepA, voffA);
;             PG8_WAIT_V(8); PG8_WAIT_L(0); PG8_BAR; PG8_MMA(0, 0, At, B0); PG8_MMA(0, 1, At, B1); PG8_BAR; PG8_SCHED;
	s_setprio 1
	s_waitcnt lgkmcnt(0)
	v_mfma_f32_16x16x32_bf16 v[68:71], v[72:75], v[168:171], v[68:71]
	v_mfma_f32_16x16x32_bf16 v[68:71], v[76:79], v[172:175], v[68:71]
	v_mfma_f32_16x16x32_bf16 v[64:67], v[80:83], v[168:171], v[64:67]
	v_mfma_f32_16x16x32_bf16 v[64:67], v[88:91], v[172:175], v[64:67]
	v_mfma_f32_16x16x32_bf16 v[52:55], v[72:75], v[176:179], v[52:55]
	v_mfma_f32_16x16x32_bf16 v[52:55], v[76:79], v[186:189], v[52:55]
	v_mfma_f32_16x16x32_bf16 v[48:51], v[80:83], v[176:179], v[48:51]
	v_mfma_f32_16x16x32_bf16 v[48:51], v[88:91], v[186:189], v[48:51]
	v_mfma_f32_16x16x32_bf16 v[34:37], v[72:75], v[200:203], v[36:39]
	v_mfma_f32_16x16x32_bf16 v[34:37], v[76:79], v[204:207], v[34:37]
	v_mfma_f32_16x16x32_bf16 v[26:29], v[80:83], v[200:203], v[26:29]
	v_mfma_f32_16x16x32_bf16 v[26:29], v[88:91], v[204:207], v[26:29]
	v_mfma_f32_16x16x32_bf16 v[14:17], v[72:75], v[208:211], v[14:17]
	v_mfma_f32_16x16x32_bf16 v[14:17], v[76:79], v[212:215], v[14:17]
	v_mfma_f32_16x16x32_bf16 v[10:13], v[80:83], v[208:211], v[10:13]
	v_mfma_f32_16x16x32_bf16 v[10:13], v[88:91], v[212:215], v[10:13]
	s_setprio 0
	s_setprio 1
	v_mfma_f32_16x16x32_bf16 v[60:63], v[152:155], v[168:171], v[60:63]
	v_mfma_f32_16x16x32_bf16 v[60:63], v[156:159], v[172:175], v[60:63]
	v_mfma_f32_16x16x32_bf16 v[56:59], v[160:163], v[168:171], v[56:59]
	v_mfma_f32_16x16x32_bf16 v[56:59], v[164:167], v[172:175], v[56:59]
	v_mfma_f32_16x16x32_bf16 v[44:47], v[152:155], v[176:179], v[44:47]
	v_mfma_f32_16x16x32_bf16 v[44:47], v[156:159], v[186:189], v[44:47]
	v_mfma_f32_16x16x32_bf16 v[38:41], v[160:163], v[176:179], v[40:43]
	v_mfma_f32_16x16x32_bf16 v[40:43], v[164:167], v[186:189], v[38:41]
	v_mfma_f32_16x16x32_bf16 v[22:25], v[152:155], v[200:203], v[22:25]
	v_mfma_f32_16x16x32_bf16 v[22:25], v[156:159], v[204:207], v[22:25]
	v_mfma_f32_16x16x32_bf16 v[18:21], v[160:163], v[200:203], v[18:21]
	v_mfma_f32_16x16x32_bf16 v[18:21], v[164:167], v[204:207], v[18:21]
	v_mfma_f32_16x16x32_bf16 v[6:9], v[152:155], v[208:211], v[6:9]
	v_mfma_f32_16x16x32_bf16 v[6:9], v[156:159], v[212:215], v[6:9]
	v_mfma_f32_16x16x32_bf16 v[2:5], v[160:163], v[208:211], v[2:5]
	v_mfma_f32_16x16x32_bf16 v[2:5], v[164:167], v[212:215], v[2:5]
	s_setprio 0
	s_barrier
	s_add_i32 s27, 0, 0x18000
	v_add_u32_e32 v32, s27, v239
	s_add_i32 s33, 0, 0x1c000
	ds_read_b128 v[72:75], v32
	ds_read_b128 v[76:79], v32 offset:1024
	ds_read_b128 v[80:83], v32 offset:2048
	ds_read_b128 v[88:91], v32 offset:3072
	v_add_u32_e32 v32, s33, v239
	ds_read_b128 v[152:155], v32
	ds_read_b128 v[156:159], v32 offset:1024
	ds_read_b128 v[160:163], v32 offset:2048
	ds_read_b128 v[164:167], v32 offset:3072
	s_add_u32 s28, s92, 0x200000
	s_addc_u32 s29, s93, 0
	s_mov_b32 m0, s42
	v_lshl_add_u64 v[38:39], s[28:29], 0, v[30:31]
	ds_read_b128 v[168:171], v251 offset:32768
	ds_read_b128 v[172:175], v251 offset:33792
	ds_read_b128 v[176:179], v251 offset:34816
	ds_read_b128 v[186:189], v251 offset:35840
	ds_read_b128 v[200:203], v251 offset:36864
	ds_read_b128 v[204:207], v251 offset:37888
	ds_read_b128 v[208:211], v251 offset:38912
	ds_read_b128 v[212:215], v251 offset:39936
	global_load_lds_dwordx4 v[38:39], off
	v_lshl_add_u64 v[38:39], s[28:29], 0, v[180:181]
	s_mov_b32 m0, s41
	s_nop 0
	global_load_lds_dwordx4 v[38:39], off
	s_waitcnt vmcnt(8)
	s_waitcnt lgkmcnt(0)
	s_barrier
	s_setprio 1
	s_waitcnt lgkmcnt(0)
	v_mfma_f32_16x16x32_bf16 v[84:87], v[72:75], v[168:171], v[84:87]
	v_mfma_f32_16x16x32_bf16 v[84:87], v[76:79], v[172:175], v[84:87]
	v_mfma_f32_16x16x32_bf16 v[148:151], v[80:83], v[168:171], v[148:151]
	v_mfma_f32_16x16x32_bf16 v[148:151], v[88:91], v[172:175], v[148:151]
	v_mfma_f32_16x16x32_bf16 v[136:139], v[72:75], v[176:179], v[136:139]
	v_mfma_f32_16x16x32_bf16 v[136:139], v[76:79], v[186:189], v[136:139]
	v_mfma_f32_16x16x32_bf16 v[132:135], v[80:83], v[176:179], v[132:135]
	v_mfma_f32_16x16x32_bf16 v[132:135], v[88:91], v[186:189], v[132:135]
	v_mfma_f32_16x16x32_bf16 v[120:123], v[72:75], v[200:203], v[120:123]
	v_mfma_f32_16x16x32_bf16 v[120:123], v[76:79], v[204:207], v[120:123]
	v_mfma_f32_16x16x32_bf16 v[116:119], v[80:83], v[200:203], v[116:119]
	v_mfma_f32_16x16x32_bf16 v[116:119], v[88:91], v[204:207], v[116:119]
	v_mfma_f32_16x16x32_bf16 v[104:107], v[72:75], v[208:211], v[104:107]
	v_mfma_f32_16x16x32_bf16 v[104:107], v[76:79], v[212:215], v[104:107]
	v_mfma_f32_16x16x32_bf16 v[100:103], v[80:83], v[208:211], v[100:103]
	v_mfma_f32_16x16x32_bf16 v[100:103], v[88:91], v[212:215], v[100:103]
	s_setprio 0
	s_setprio 1
	v_mfma_f32_16x16x32_bf16 v[144:147], v[152:155], v[168:171], v[144:147]
	v_mfma_f32_16x16x32_bf16 v[144:147], v[156:159], v[172:175], v[144:147]
	v_mfma_f32_16x16x32_bf16 v[140:143], v[160:163], v[168:171], v[140:143]
	v_mfma_f32_16x16x32_bf16 v[140:143], v[164:167], v[172:175], v[140:143]
	v_mfma_f32_16x16x32_bf16 v[128:131], v[152:155], v[176:179], v[128:131]
	v_mfma_f32_16x16x32_bf16 v[128:131], v[156:159], v[186:189], v[128:131]
	v_mfma_f32_16x16x32_bf16 v[124:127], v[160:163], v[176:179], v[124:127]
	v_mfma_f32_16x16x32_bf16 v[124:127], v[164:167], v[186:189], v[124:127]
	v_mfma_f32_16x16x32_bf16 v[112:115], v[152:155], v[200:203], v[112:115]
	v_mfma_f32_16x16x32_bf16 v[112:115], v[156:159], v[204:207], v[112:115]
	v_mfma_f32_16x16x32_bf16 v[108:111], v[160:163], v[200:203], v[108:111]
	v_mfma_f32_16x16x32_bf16 v[108:111], v[164:167], v[204:207], v[108:111]
	v_mfma_f32_16x16x32_bf16 v[96:99], v[152:155], v[208:211], v[96:99]
	v_mfma_f32_16x16x32_bf16 v[96:99], v[156:159], v[212:215], v[96:99]
	v_mfma_f32_16x16x32_bf16 v[92:95], v[160:163], v[208:211], v[92:95]
	v_mfma_f32_16x16x32_bf16 v[92:95], v[164:167], v[212:215], v[92:95]
	s_setprio 0
	s_barrier
; #define PG8_STAGE(bufoff, gbase, voff) do { _Pragma("unroll") for (int _i = 0; _i < 2; ++_i) \
;         __builtin_amdgcn_global_load_lds((const unsigned*)((const char*)(gbase) + (voff)[_i]), (PG8_LAS unsigned*)(lds + (bufoff) + ldsw + _i * 8192), 16, 0, 0); } while (0)
; #define PG8_LDA(dst, b, h) do { _Pragma("unroll") for (int m = 0; m < 4; ++m) _Pragma("unroll") for (int k = 0; k < 2; ++k) dst[m][k] = *(const PG8_LAS bf16x8*)(lds + PG8_SA(b, h) + aoff + m * 2048 + k * 1024); } while (0)
; #define PG8_MMA(ai, bj, At, Bt) do { __builtin_amdgcn_s_setprio(1); _Pragma("unroll") for (int m = 0; m < 4; ++m) _Pragma("unroll") for (int n = 0; n < 2; ++n) _Pragma("unroll") for (int k = 0; k < 2; ++k) \
;         acc[ai][bj][m][n] = __builtin_amdgcn_mfma_f32_16x16x32_bf16(Bt[n][k], At[m][k], acc[ai][bj][m][n], 0, 0, 0); __builtin_amdgcn_s_setprio(0); } while (0)
; #define PG8_WAIT_V(n) asm volatile("s_waitcnt vmcnt(" #n ")" ::: "memory")
; #define PG8_WAIT_L(n) asm volatile("s_waitcnt lgkmcnt(" #n ")" ::: "memory")
; #define PG8_BAR __builtin_amdgcn_s_barrier()
; #define PG8_SCHED __builtin_amdgcn_sched_barrier(0)
;     ...
;         for (int t = 0; t < nt; t += 2) {
;             const bool last = (t == nt - 2);
;             const char* a1 = cA + (size_t)(t + 1) * kstep;
;             const char* a2 = last ? nA : cA + (size_t)(t + 2) * kstep; const char* b2 = last ? nB : cB + (size_t)(t + 2) * kstep;
;     ...
;             PG8_LDA(At, 1, 1); PG8_STAGE(PG8_SB(1, 0), b3, voffB); PG8_STAGE(PG8_SB(1, 1), b3 + hstep, voffB); PG8_STAGE(PG8_SA(1, 0), a3, voffA);
;             PG8_WAIT_V(8); PG8_WAIT_L(0); PG8_BAR; PG8_MMA(1, 0, At, B0); PG8_MMA(1, 1, At, B1); PG8_BAR; PG8_SCHED;
	s_add_i32 s27, s27, s3
	v_lshl_add_u64 v[38:39], v[190:191], 0, s[64:65]
	s_mov_b32 m0, s27
	ds_read_b128 v[168:171], v251 offset:49152
	ds_read_b128 v[172:175], v251 offset:50176
	ds_read_b128 v[176:179], v251 offset:51200
	ds_read_b128 v[186:189], v251 offset:52224
	ds_read_b128 v[200:203], v251 offset:53248
	ds_read_b128 v[204:207], v251 offset:54272
	ds_read_b128 v[208:211], v251 offset:55296
	ds_read_b128 v[212:215], v251 offset:56320
	global_load_lds_dwordx4 v[38:39], off
	s_add_i32 m0, s27, 0x2000
	s_add_u32 s28, s38, 0x200080
	v_lshl_add_u64 v[38:39], v[216:217], 0, s[64:65]
	s_addc_u32 s29, s39, 0
	s_add_i32 s27, s33, s3
	global_load_lds_dwordx4 v[38:39], off
	v_lshl_add_u64 v[38:39], s[28:29], 0, v[30:31]
	s_mov_b32 m0, s27
	s_nop 0
	global_load_lds_dwordx4 v[38:39], off
	v_lshl_add_u64 v[38:39], s[28:29], 0, v[180:181]
	s_add_i32 m0, s27, 0x2000
	s_nop 0
	global_load_lds_dwordx4 v[38:39], off
	v_lshl_add_u64 v[38:39], v[218:219], 0, s[64:65]
	s_mov_b32 m0, s53
	s_nop 0
	global_load_lds_dwordx4 v[38:39], off
	v_lshl_add_u64 v[38:39], v[220:221], 0, s[64:65]
	s_mov_b32 m0, s10
	s_nop 0
	global_load_lds_dwordx4 v[38:39], off
	s_waitcnt vmcnt(8)
	s_waitcnt lgkmcnt(0)
	s_barrier
	s_setprio 1
	s_waitcnt lgkmcnt(0)
	v_mfma_f32_16x16x32_bf16 v[68:71], v[72:75], v[168:171], v[68:71]
	v_mfma_f32_16x16x32_bf16 v[68:71], v[76:79], v[172:175], v[68:71]
	v_mfma_f32_16x16x32_bf16 v[64:67], v[80:83], v[168:171], v[64:67]
	v_mfma_f32_16x16x32_bf16 v[64:67], v[88:91], v[172:175], v[64:67]
	v_mfma_f32_16x16x32_bf16 v[52:55], v[72:75], v[176:179], v[52:55]
	v_mfma_f32_16x16x32_bf16 v[52:55], v[76:79], v[186:189], v[52:55]
	v_mfma_f32_16x16x32_bf16 v[48:51], v[80:83], v[176:179], v[48:51]
	v_mfma_f32_16x16x32_bf16 v[48:51], v[88:91], v[186:189], v[48:51]
	v_mfma_f32_16x16x32_bf16 v[34:37], v[72:75], v[200:203], v[34:37]
	v_mfma_f32_16x16x32_bf16 v[36:39], v[76:79], v[204:207], v[34:37]
	v_mfma_f32_16x16x32_bf16 v[26:29], v[80:83], v[200:203], v[26:29]
	v_mfma_f32_16x16x32_bf16 v[26:29], v[88:91], v[204:207], v[26:29]
	v_mfma_f32_16x16x32_bf16 v[14:17], v[72:75], v[208:211], v[14:17]
	v_mfma_f32_16x16x32_bf16 v[14:17], v[76:79], v[212:215], v[14:17]
	v_mfma_f32_16x16x32_bf16 v[10:13], v[80:83], v[208:211], v[10:13]
	v_mfma_f32_16x16x32_bf16 v[10:13], v[88:91], v[212:215], v[10:13]
	s_setprio 0
	s_setprio 1
	v_mfma_f32_16x16x32_bf16 v[60:63], v[152:155], v[168:171], v[60:63]
	v_mfma_f32_16x16x32_bf16 v[60:63], v[156:159], v[172:175], v[60:63]
	v_mfma_f32_16x16x32_bf16 v[56:59], v[160:163], v[168:171], v[56:59]
	v_mfma_f32_16x16x32_bf16 v[56:59], v[164:167], v[172:175], v[56:59]
	v_mfma_f32_16x16x32_bf16 v[44:47], v[152:155], v[176:179], v[44:47]
	v_mfma_f32_16x16x32_bf16 v[44:47], v[156:159], v[186:189], v[44:47]
	v_mfma_f32_16x16x32_bf16 v[40:43], v[160:163], v[176:179], v[40:43]
	v_mfma_f32_16x16x32_bf16 v[40:43], v[164:167], v[186:189], v[40:43]
	v_mfma_f32_16x16x32_bf16 v[22:25], v[152:155], v[200:203], v[22:25]
	v_mfma_f32_16x16x32_bf16 v[22:25], v[156:159], v[204:207], v[22:25]
	v_mfma_f32_16x16x32_bf16 v[18:21], v[160:163], v[200:203], v[18:21]
	v_mfma_f32_16x16x32_bf16 v[18:21], v[164:167], v[204:207], v[18:21]
	v_mfma_f32_16x16x32_bf16 v[6:9], v[152:155], v[208:211], v[6:9]
	v_mfma_f32_16x16x32_bf16 v[6:9], v[156:159], v[212:215], v[6:9]
	v_mfma_f32_16x16x32_bf16 v[2:5], v[160:163], v[208:211], v[2:5]
	v_mfma_f32_16x16x32_bf16 v[2:5], v[164:167], v[212:215], v[2:5]
	s_setprio 0
	s_barrier
	s_add_i32 s27, s25, 2
	s_add_u32 s9, s9, 0x100
	s_addc_u32 s23, s23, 0
	s_cmp_ge_i32 s25, s40
	s_mov_b64 s[28:29], s[30:31]
	s_mov_b32 s25, s27
	s_cbranch_scc0 .LBB0_1454
	s_and_b64 vcc, exec, s[16:17]
	s_cbranch_vccz .LBB0_1457
	s_barrier
